# FF2-L0 output section regenerated (H pass + X pass); waves 1-7 carry their 16 residual-stream stores across the grid barrier, wave 0 stores X first; barrier prefetches of waves 1-7 unwaited
# baseline (speedup 1.0000x reference)
; #define LAS __attribute__((address_space(3)))
; __device__ __forceinline__ unsigned cvt_pk_bf16(float lo, float hi) { const f32x2 v = {lo, hi}; const bf16x2_t b = __builtin_convertvector(v, bf16x2_t); return __builtin_bit_cast(unsigned, b); }
;     __device__ __forceinline__ void epi(AccT& acc, const Unit& u, LAS unsigned char* lds, int wr, int wc, int fr, int fq) const {
;     ...
;             LAS float* svl = Sl + 320; LAS float* tvl = svl + 256;
;             if (tid < 256) { const int c = u.pn * 256 + tid; svl[tid] = wf[c] * (1.f + shp[(size_t)b * 6 * D + D + c]); tvl[tid] = shp[(size_t)b * 6 * D + c]; }
;             asm volatile("s_waitcnt vmcnt(0) lgkmcnt(0)" ::: "memory"); __builtin_amdgcn_s_barrier(); asm volatile("" ::: "memory");
;             const int cl = wc * 64 + 8 * fq, colp = u.pn * 256 + wc * 64 + (lo ? 0 : 32) + 8 * fq; bf16_t* XHw = (bf16_t*)X;
; #pragma unroll
;             for (int ai = 0; ai < 2; ++ai)
; #pragma unroll
;                 for (int m = 0; m < 4; ++m) { const int r = ai * 128 + wr * 64 + m * 16 + fr; const float rs = bad ? qnan : Sl[r];
;                     const size_t rowA = (size_t)(u.pm * 256 + ai * 128 + wr * 64 + m * 16 + (fr & 7)); u32x4 p[2], q[2];
; #pragma unroll
;                     for (int bj = 0; bj < 2; ++bj) { const f32x4 x0 = acc[ai][bj][m][0], x1 = acc[ai][bj][m][1];
;                         const f32x4 h0 = x0 * rs * *(const LAS f32x4*)(svl + cl + bj * 32) + *(const LAS f32x4*)(tvl + cl + bj * 32), h1 = x1 * rs * *(const LAS f32x4*)(svl + cl + bj * 32 + 4) + *(const LAS f32x4*)(tvl + cl + bj * 32 + 4);
;                         p[bj].x = cvt_pk_bf16(h0[0], h0[1]); p[bj].y = cvt_pk_bf16(h0[2], h0[3]); p[bj].z = cvt_pk_bf16(h1[0], h1[1]); p[bj].w = cvt_pk_bf16(h1[2], h1[3]);
;                         q[bj].x = cvt_pk_bf16(x0[0], x0[1]); q[bj].y = cvt_pk_bf16(x0[2], x0[3]); q[bj].z = cvt_pk_bf16(x1[0], x1[1]); q[bj].w = cvt_pk_bf16(x1[2], x1[3]); }
;                     const u32x4 rq0 = ror8_u4(q[0]), rq1 = ror8_u4(q[1]), rp0 = ror8_u4(p[0]), rp1 = ror8_u4(p[1]);
;                     store16_wt(XHw + rowA * (2 * D) + colp, lo ? q[0] : rq1); store16_wt(XHw + (rowA + 8) * (2 * D) + colp, lo ? rq0 : q[1]);
;                     store16_wt(H + rowA * D + colp, lo ? p[0] : rp1); store16_wt(H + (rowA + 8) * D + colp, lo ? rp0 : p[1]); }
.LBB0_683:
	s_or_b64 exec, exec, s[22:23]
	s_waitcnt vmcnt(0) lgkmcnt(0)
	s_barrier
	s_waitcnt lgkmcnt(0)
	s_cmp_lg_u32 s90, 0
	s_cbranch_scc1 .Lxd20_h
	v_add_u32_e32 v172, v178, v207
	v_ashrrev_i32_e32 v173, 31, v172
	v_lshlrev_b64 v[172:173], 1, v[172:173]
	v_lshl_add_u64 v[248:249], s[84:85], 0, v[172:173]
	v_or_b32_e32 v174, s41, v208
	s_mov_b32 s88, 0x8000
	s_mov_b32 s89, 0
	v_cvt_pk_bf16_f32 v228, v140, v141
	v_cvt_pk_bf16_f32 v229, v142, v143
	v_cvt_pk_bf16_f32 v230, v136, v137
	v_cvt_pk_bf16_f32 v231, v138, v139
	v_cvt_pk_bf16_f32 v232, v132, v133
	v_cvt_pk_bf16_f32 v233, v134, v135
	v_cvt_pk_bf16_f32 v234, v180, v181
	v_cvt_pk_bf16_f32 v235, v168, v169
	v_add_u32_e32 v172, 0, v174
	v_mov_b32_e32 v173, 0
	v_lshlrev_b64 v[250:251], 12, v[172:173]
	v_lshl_add_u64 v[250:251], v[248:249], 0, v[250:251]
	v_mov_b32_dpp v236, v232 row_ror:8 row_mask:0xf bank_mask:0xf bound_ctrl:1
	v_mov_b32_dpp v237, v233 row_ror:8 row_mask:0xf bank_mask:0xf bound_ctrl:1
	v_mov_b32_dpp v238, v234 row_ror:8 row_mask:0xf bank_mask:0xf bound_ctrl:1
	v_mov_b32_dpp v239, v235 row_ror:8 row_mask:0xf bank_mask:0xf bound_ctrl:1
	v_cndmask_b32_e64 v240, v236, v228, s[18:19]
	v_cndmask_b32_e64 v241, v237, v229, s[18:19]
	v_cndmask_b32_e64 v242, v238, v230, s[18:19]
	v_cndmask_b32_e64 v243, v239, v231, s[18:19]
	global_store_dwordx4 v[250:251], v[240:243], off sc1
	s_nop 1
	v_mov_b32_dpp v236, v228 row_ror:8 row_mask:0xf bank_mask:0xf bound_ctrl:1
	v_mov_b32_dpp v237, v229 row_ror:8 row_mask:0xf bank_mask:0xf bound_ctrl:1
	v_mov_b32_dpp v238, v230 row_ror:8 row_mask:0xf bank_mask:0xf bound_ctrl:1
	v_mov_b32_dpp v239, v231 row_ror:8 row_mask:0xf bank_mask:0xf bound_ctrl:1
	v_cndmask_b32_e64 v244, v232, v236, s[18:19]
	v_cndmask_b32_e64 v245, v233, v237, s[18:19]
	v_cndmask_b32_e64 v246, v234, v238, s[18:19]
	v_cndmask_b32_e64 v247, v235, v239, s[18:19]
	v_lshl_add_u64 v[250:251], v[250:251], 0, s[88:89]
	global_store_dwordx4 v[250:251], v[244:247], off sc1
	s_nop 1
	v_cvt_pk_bf16_f32 v228, v170, v171
	v_cvt_pk_bf16_f32 v229, v164, v165
	v_cvt_pk_bf16_f32 v230, v188, v189
	v_cvt_pk_bf16_f32 v231, v184, v185
	v_cvt_pk_bf16_f32 v232, v182, v183
	v_cvt_pk_bf16_f32 v233, v166, v167
	v_cvt_pk_bf16_f32 v234, v190, v191
	v_cvt_pk_bf16_f32 v235, v186, v187
	v_add_u32_e32 v172, 16, v174
	v_mov_b32_e32 v173, 0
	v_lshlrev_b64 v[250:251], 12, v[172:173]
	v_lshl_add_u64 v[250:251], v[248:249], 0, v[250:251]
	v_mov_b32_dpp v236, v232 row_ror:8 row_mask:0xf bank_mask:0xf bound_ctrl:1
	v_mov_b32_dpp v237, v233 row_ror:8 row_mask:0xf bank_mask:0xf bound_ctrl:1
	v_mov_b32_dpp v238, v234 row_ror:8 row_mask:0xf bank_mask:0xf bound_ctrl:1
	v_mov_b32_dpp v239, v235 row_ror:8 row_mask:0xf bank_mask:0xf bound_ctrl:1
	v_cndmask_b32_e64 v240, v236, v228, s[18:19]
	v_cndmask_b32_e64 v241, v237, v229, s[18:19]
	v_cndmask_b32_e64 v242, v238, v230, s[18:19]
	v_cndmask_b32_e64 v243, v239, v231, s[18:19]
	global_store_dwordx4 v[250:251], v[240:243], off sc1
	s_nop 1
	v_mov_b32_dpp v236, v228 row_ror:8 row_mask:0xf bank_mask:0xf bound_ctrl:1
	v_mov_b32_dpp v237, v229 row_ror:8 row_mask:0xf bank_mask:0xf bound_ctrl:1
	v_mov_b32_dpp v238, v230 row_ror:8 row_mask:0xf bank_mask:0xf bound_ctrl:1
	v_mov_b32_dpp v239, v231 row_ror:8 row_mask:0xf bank_mask:0xf bound_ctrl:1
	v_cndmask_b32_e64 v244, v232, v236, s[18:19]
	v_cndmask_b32_e64 v245, v233, v237, s[18:19]
	v_cndmask_b32_e64 v246, v234, v238, s[18:19]
	v_cndmask_b32_e64 v247, v235, v239, s[18:19]
	v_lshl_add_u64 v[250:251], v[250:251], 0, s[88:89]
	global_store_dwordx4 v[250:251], v[244:247], off sc1
	s_nop 1
	v_cvt_pk_bf16_f32 v228, v130, v131
	v_cvt_pk_bf16_f32 v229, v128, v129
	v_cvt_pk_bf16_f32 v230, v160, v161
	v_cvt_pk_bf16_f32 v231, v158, v159
	v_cvt_pk_bf16_f32 v232, v156, v157
	v_cvt_pk_bf16_f32 v233, v148, v149
	v_cvt_pk_bf16_f32 v234, v162, v163
	v_cvt_pk_bf16_f32 v235, v150, v151
	v_add_u32_e32 v172, 32, v174
	v_mov_b32_e32 v173, 0
	v_lshlrev_b64 v[250:251], 12, v[172:173]
	v_lshl_add_u64 v[250:251], v[248:249], 0, v[250:251]
	v_mov_b32_dpp v236, v232 row_ror:8 row_mask:0xf bank_mask:0xf bound_ctrl:1
	v_mov_b32_dpp v237, v233 row_ror:8 row_mask:0xf bank_mask:0xf bound_ctrl:1
	v_mov_b32_dpp v238, v234 row_ror:8 row_mask:0xf bank_mask:0xf bound_ctrl:1
	v_mov_b32_dpp v239, v235 row_ror:8 row_mask:0xf bank_mask:0xf bound_ctrl:1
	v_cndmask_b32_e64 v240, v236, v228, s[18:19]
	v_cndmask_b32_e64 v241, v237, v229, s[18:19]
	v_cndmask_b32_e64 v242, v238, v230, s[18:19]
	v_cndmask_b32_e64 v243, v239, v231, s[18:19]
	global_store_dwordx4 v[250:251], v[240:243], off sc1
	s_nop 1
	v_mov_b32_dpp v236, v228 row_ror:8 row_mask:0xf bank_mask:0xf bound_ctrl:1
	v_mov_b32_dpp v237, v229 row_ror:8 row_mask:0xf bank_mask:0xf bound_ctrl:1
	v_mov_b32_dpp v238, v230 row_ror:8 row_mask:0xf bank_mask:0xf bound_ctrl:1
	v_mov_b32_dpp v239, v231 row_ror:8 row_mask:0xf bank_mask:0xf bound_ctrl:1
	v_cndmask_b32_e64 v244, v232, v236, s[18:19]
	v_cndmask_b32_e64 v245, v233, v237, s[18:19]
	v_cndmask_b32_e64 v246, v234, v238, s[18:19]
	v_cndmask_b32_e64 v247, v235, v239, s[18:19]
	v_lshl_add_u64 v[250:251], v[250:251], 0, s[88:89]
	global_store_dwordx4 v[250:251], v[244:247], off sc1
	s_nop 1
	v_cvt_pk_bf16_f32 v228, v84, v85
	v_cvt_pk_bf16_f32 v229, v80, v81
	v_cvt_pk_bf16_f32 v230, v92, v93
	v_cvt_pk_bf16_f32 v231, v88, v89
	v_cvt_pk_bf16_f32 v232, v86, v87
	v_cvt_pk_bf16_f32 v233, v82, v83
	v_cvt_pk_bf16_f32 v234, v94, v95
	v_cvt_pk_bf16_f32 v235, v90, v91
	v_add_u32_e32 v172, 48, v174
	v_mov_b32_e32 v173, 0
	v_lshlrev_b64 v[250:251], 12, v[172:173]
	v_lshl_add_u64 v[250:251], v[248:249], 0, v[250:251]
	v_mov_b32_dpp v236, v232 row_ror:8 row_mask:0xf bank_mask:0xf bound_ctrl:1
; #define LAS __attribute__((address_space(3)))
; __device__ __forceinline__ unsigned cvt_pk_bf16(float lo, float hi) { const f32x2 v = {lo, hi}; const bf16x2_t b = __builtin_convertvector(v, bf16x2_t); return __builtin_bit_cast(unsigned, b); }
; __device__ __forceinline__ void store16_wt(void* p, u32x4 v) { asm volatile("global_store_dwordx4 %0, %1, off sc1\n\ts_nop 1" :: "v"(p), "v"(v) : "memory"); }
; __device__ __forceinline__ u32x4 ror8_u4(u32x4 v) { const unsigned a = ror8_u(v.x), b = ror8_u(v.y), c = ror8_u(v.z), d = ror8_u(v.w); return (u32x4){a, b, c, d}; }
;     __device__ __forceinline__ void epi(AccT& acc, const Unit& u, LAS unsigned char* lds, int wr, int wc, int fr, int fq) const {
;     ...
;             const int cl = wc * 64 + 8 * fq, colp = u.pn * 256 + wc * 64 + (lo ? 0 : 32) + 8 * fq; bf16_t* XHw = (bf16_t*)X;
; #pragma unroll
;             for (int ai = 0; ai < 2; ++ai)
; #pragma unroll
;                 for (int m = 0; m < 4; ++m) { const int r = ai * 128 + wr * 64 + m * 16 + fr; const float rs = bad ? qnan : Sl[r];
;                     const size_t rowA = (size_t)(u.pm * 256 + ai * 128 + wr * 64 + m * 16 + (fr & 7)); u32x4 p[2], q[2];
; #pragma unroll
;                     for (int bj = 0; bj < 2; ++bj) { const f32x4 x0 = acc[ai][bj][m][0], x1 = acc[ai][bj][m][1];
;                         const f32x4 h0 = x0 * rs * *(const LAS f32x4*)(svl + cl + bj * 32) + *(const LAS f32x4*)(tvl + cl + bj * 32), h1 = x1 * rs * *(const LAS f32x4*)(svl + cl + bj * 32 + 4) + *(const LAS f32x4*)(tvl + cl + bj * 32 + 4);
;                         p[bj].x = cvt_pk_bf16(h0[0], h0[1]); p[bj].y = cvt_pk_bf16(h0[2], h0[3]); p[bj].z = cvt_pk_bf16(h1[0], h1[1]); p[bj].w = cvt_pk_bf16(h1[2], h1[3]);
;                         q[bj].x = cvt_pk_bf16(x0[0], x0[1]); q[bj].y = cvt_pk_bf16(x0[2], x0[3]); q[bj].z = cvt_pk_bf16(x1[0], x1[1]); q[bj].w = cvt_pk_bf16(x1[2], x1[3]); }
;                     const u32x4 rq0 = ror8_u4(q[0]), rq1 = ror8_u4(q[1]), rp0 = ror8_u4(p[0]), rp1 = ror8_u4(p[1]);
;                     store16_wt(XHw + rowA * (2 * D) + colp, lo ? q[0] : rq1); store16_wt(XHw + (rowA + 8) * (2 * D) + colp, lo ? rq0 : q[1]);
;                     store16_wt(H + rowA * D + colp, lo ? p[0] : rp1); store16_wt(H + (rowA + 8) * D + colp, lo ? rp0 : p[1]); }
	v_mov_b32_dpp v237, v233 row_ror:8 row_mask:0xf bank_mask:0xf bound_ctrl:1
	v_mov_b32_dpp v238, v234 row_ror:8 row_mask:0xf bank_mask:0xf bound_ctrl:1
	v_mov_b32_dpp v239, v235 row_ror:8 row_mask:0xf bank_mask:0xf bound_ctrl:1
	v_cndmask_b32_e64 v240, v236, v228, s[18:19]
	v_cndmask_b32_e64 v241, v237, v229, s[18:19]
	v_cndmask_b32_e64 v242, v238, v230, s[18:19]
	v_cndmask_b32_e64 v243, v239, v231, s[18:19]
	global_store_dwordx4 v[250:251], v[240:243], off sc1
	s_nop 1
	v_mov_b32_dpp v236, v228 row_ror:8 row_mask:0xf bank_mask:0xf bound_ctrl:1
	v_mov_b32_dpp v237, v229 row_ror:8 row_mask:0xf bank_mask:0xf bound_ctrl:1
	v_mov_b32_dpp v238, v230 row_ror:8 row_mask:0xf bank_mask:0xf bound_ctrl:1
	v_mov_b32_dpp v239, v231 row_ror:8 row_mask:0xf bank_mask:0xf bound_ctrl:1
	v_cndmask_b32_e64 v244, v232, v236, s[18:19]
	v_cndmask_b32_e64 v245, v233, v237, s[18:19]
	v_cndmask_b32_e64 v246, v234, v238, s[18:19]
	v_cndmask_b32_e64 v247, v235, v239, s[18:19]
	v_lshl_add_u64 v[250:251], v[250:251], 0, s[88:89]
	global_store_dwordx4 v[250:251], v[244:247], off sc1
	s_nop 1
	v_cvt_pk_bf16_f32 v228, v60, v61
	v_cvt_pk_bf16_f32 v229, v62, v63
	v_cvt_pk_bf16_f32 v230, v56, v57
	v_cvt_pk_bf16_f32 v231, v58, v59
	v_cvt_pk_bf16_f32 v232, v52, v53
	v_cvt_pk_bf16_f32 v233, v54, v55
	v_cvt_pk_bf16_f32 v234, v48, v49
	v_cvt_pk_bf16_f32 v235, v50, v51
	v_add_u32_e32 v172, 0x80, v174
	v_mov_b32_e32 v173, 0
	v_lshlrev_b64 v[250:251], 12, v[172:173]
	v_lshl_add_u64 v[250:251], v[248:249], 0, v[250:251]
	v_mov_b32_dpp v236, v232 row_ror:8 row_mask:0xf bank_mask:0xf bound_ctrl:1
	v_mov_b32_dpp v237, v233 row_ror:8 row_mask:0xf bank_mask:0xf bound_ctrl:1
	v_mov_b32_dpp v238, v234 row_ror:8 row_mask:0xf bank_mask:0xf bound_ctrl:1
	v_mov_b32_dpp v239, v235 row_ror:8 row_mask:0xf bank_mask:0xf bound_ctrl:1
	v_cndmask_b32_e64 v240, v236, v228, s[18:19]
	v_cndmask_b32_e64 v241, v237, v229, s[18:19]
	v_cndmask_b32_e64 v242, v238, v230, s[18:19]
	v_cndmask_b32_e64 v243, v239, v231, s[18:19]
	global_store_dwordx4 v[250:251], v[240:243], off sc1
	s_nop 1
	v_mov_b32_dpp v236, v228 row_ror:8 row_mask:0xf bank_mask:0xf bound_ctrl:1
	v_mov_b32_dpp v237, v229 row_ror:8 row_mask:0xf bank_mask:0xf bound_ctrl:1
	v_mov_b32_dpp v238, v230 row_ror:8 row_mask:0xf bank_mask:0xf bound_ctrl:1
	v_mov_b32_dpp v239, v231 row_ror:8 row_mask:0xf bank_mask:0xf bound_ctrl:1
	v_cndmask_b32_e64 v244, v232, v236, s[18:19]
	v_cndmask_b32_e64 v245, v233, v237, s[18:19]
	v_cndmask_b32_e64 v246, v234, v238, s[18:19]
	v_cndmask_b32_e64 v247, v235, v239, s[18:19]
	v_lshl_add_u64 v[250:251], v[250:251], 0, s[88:89]
	global_store_dwordx4 v[250:251], v[244:247], off sc1
	s_nop 1
	v_cvt_pk_bf16_f32 v228, v44, v45
	v_cvt_pk_bf16_f32 v229, v46, v47
	v_cvt_pk_bf16_f32 v230, v40, v41
	v_cvt_pk_bf16_f32 v231, v42, v43
	v_cvt_pk_bf16_f32 v232, v36, v37
	v_cvt_pk_bf16_f32 v233, v38, v39
	v_cvt_pk_bf16_f32 v234, v32, v33
	v_cvt_pk_bf16_f32 v235, v34, v35
	v_add_u32_e32 v172, 0x90, v174
	v_mov_b32_e32 v173, 0
	v_lshlrev_b64 v[250:251], 12, v[172:173]
	v_lshl_add_u64 v[250:251], v[248:249], 0, v[250:251]
	v_mov_b32_dpp v236, v232 row_ror:8 row_mask:0xf bank_mask:0xf bound_ctrl:1
	v_mov_b32_dpp v237, v233 row_ror:8 row_mask:0xf bank_mask:0xf bound_ctrl:1
	v_mov_b32_dpp v238, v234 row_ror:8 row_mask:0xf bank_mask:0xf bound_ctrl:1
	v_mov_b32_dpp v239, v235 row_ror:8 row_mask:0xf bank_mask:0xf bound_ctrl:1
	v_cndmask_b32_e64 v240, v236, v228, s[18:19]
	v_cndmask_b32_e64 v241, v237, v229, s[18:19]
	v_cndmask_b32_e64 v242, v238, v230, s[18:19]
	v_cndmask_b32_e64 v243, v239, v231, s[18:19]
	global_store_dwordx4 v[250:251], v[240:243], off sc1
	s_nop 1
	v_mov_b32_dpp v236, v228 row_ror:8 row_mask:0xf bank_mask:0xf bound_ctrl:1
	v_mov_b32_dpp v237, v229 row_ror:8 row_mask:0xf bank_mask:0xf bound_ctrl:1
	v_mov_b32_dpp v238, v230 row_ror:8 row_mask:0xf bank_mask:0xf bound_ctrl:1
	v_mov_b32_dpp v239, v231 row_ror:8 row_mask:0xf bank_mask:0xf bound_ctrl:1
	v_cndmask_b32_e64 v244, v232, v236, s[18:19]
	v_cndmask_b32_e64 v245, v233, v237, s[18:19]
	v_cndmask_b32_e64 v246, v234, v238, s[18:19]
	v_cndmask_b32_e64 v247, v235, v239, s[18:19]
	v_lshl_add_u64 v[250:251], v[250:251], 0, s[88:89]
	global_store_dwordx4 v[250:251], v[244:247], off sc1
	s_nop 1
	v_cvt_pk_bf16_f32 v228, v28, v29
	v_cvt_pk_bf16_f32 v229, v30, v31
	v_cvt_pk_bf16_f32 v230, v24, v25
	v_cvt_pk_bf16_f32 v231, v26, v27
	v_cvt_pk_bf16_f32 v232, v20, v21
	v_cvt_pk_bf16_f32 v233, v22, v23
	v_cvt_pk_bf16_f32 v234, v16, v17
	v_cvt_pk_bf16_f32 v235, v18, v19
	v_add_u32_e32 v172, 0xa0, v174
	v_mov_b32_e32 v173, 0
	v_lshlrev_b64 v[250:251], 12, v[172:173]
	v_lshl_add_u64 v[250:251], v[248:249], 0, v[250:251]
	v_mov_b32_dpp v236, v232 row_ror:8 row_mask:0xf bank_mask:0xf bound_ctrl:1
	v_mov_b32_dpp v237, v233 row_ror:8 row_mask:0xf bank_mask:0xf bound_ctrl:1
	v_mov_b32_dpp v238, v234 row_ror:8 row_mask:0xf bank_mask:0xf bound_ctrl:1
	v_mov_b32_dpp v239, v235 row_ror:8 row_mask:0xf bank_mask:0xf bound_ctrl:1
	v_cndmask_b32_e64 v240, v236, v228, s[18:19]
	v_cndmask_b32_e64 v241, v237, v229, s[18:19]
	v_cndmask_b32_e64 v242, v238, v230, s[18:19]
	v_cndmask_b32_e64 v243, v239, v231, s[18:19]
	global_store_dwordx4 v[250:251], v[240:243], off sc1
	s_nop 1
	v_mov_b32_dpp v236, v228 row_ror:8 row_mask:0xf bank_mask:0xf bound_ctrl:1
	v_mov_b32_dpp v237, v229 row_ror:8 row_mask:0xf bank_mask:0xf bound_ctrl:1
	v_mov_b32_dpp v238, v230 row_ror:8 row_mask:0xf bank_mask:0xf bound_ctrl:1
	v_mov_b32_dpp v239, v231 row_ror:8 row_mask:0xf bank_mask:0xf bound_ctrl:1
	v_cndmask_b32_e64 v244, v232, v236, s[18:19]
	v_cndmask_b32_e64 v245, v233, v237, s[18:19]
	v_cndmask_b32_e64 v246, v234, v238, s[18:19]
; #define LAS __attribute__((address_space(3)))
; __device__ __forceinline__ unsigned cvt_pk_bf16(float lo, float hi) { const f32x2 v = {lo, hi}; const bf16x2_t b = __builtin_convertvector(v, bf16x2_t); return __builtin_bit_cast(unsigned, b); }
; __device__ __forceinline__ void store16_wt(void* p, u32x4 v) { asm volatile("global_store_dwordx4 %0, %1, off sc1\n\ts_nop 1" :: "v"(p), "v"(v) : "memory"); }
; __device__ __forceinline__ u32x4 ror8_u4(u32x4 v) { const unsigned a = ror8_u(v.x), b = ror8_u(v.y), c = ror8_u(v.z), d = ror8_u(v.w); return (u32x4){a, b, c, d}; }
;     __device__ __forceinline__ void epi(AccT& acc, const Unit& u, LAS unsigned char* lds, int wr, int wc, int fr, int fq) const {
;     ...
;                 for (int m = 0; m < 4; ++m) { const int r = ai * 128 + wr * 64 + m * 16 + fr; const float rs = bad ? qnan : Sl[r];
;                     const size_t rowA = (size_t)(u.pm * 256 + ai * 128 + wr * 64 + m * 16 + (fr & 7)); u32x4 p[2], q[2];
; #pragma unroll
;                     for (int bj = 0; bj < 2; ++bj) { const f32x4 x0 = acc[ai][bj][m][0], x1 = acc[ai][bj][m][1];
;                         const f32x4 h0 = x0 * rs * *(const LAS f32x4*)(svl + cl + bj * 32) + *(const LAS f32x4*)(tvl + cl + bj * 32), h1 = x1 * rs * *(const LAS f32x4*)(svl + cl + bj * 32 + 4) + *(const LAS f32x4*)(tvl + cl + bj * 32 + 4);
;                         p[bj].x = cvt_pk_bf16(h0[0], h0[1]); p[bj].y = cvt_pk_bf16(h0[2], h0[3]); p[bj].z = cvt_pk_bf16(h1[0], h1[1]); p[bj].w = cvt_pk_bf16(h1[2], h1[3]);
;                         q[bj].x = cvt_pk_bf16(x0[0], x0[1]); q[bj].y = cvt_pk_bf16(x0[2], x0[3]); q[bj].z = cvt_pk_bf16(x1[0], x1[1]); q[bj].w = cvt_pk_bf16(x1[2], x1[3]); }
;                     const u32x4 rq0 = ror8_u4(q[0]), rq1 = ror8_u4(q[1]), rp0 = ror8_u4(p[0]), rp1 = ror8_u4(p[1]);
;                     store16_wt(XHw + rowA * (2 * D) + colp, lo ? q[0] : rq1); store16_wt(XHw + (rowA + 8) * (2 * D) + colp, lo ? rq0 : q[1]);
;                     store16_wt(H + rowA * D + colp, lo ? p[0] : rp1); store16_wt(H + (rowA + 8) * D + colp, lo ? rp0 : p[1]); }
	v_cndmask_b32_e64 v247, v235, v239, s[18:19]
	v_lshl_add_u64 v[250:251], v[250:251], 0, s[88:89]
	global_store_dwordx4 v[250:251], v[244:247], off sc1
	s_nop 1
	v_cvt_pk_bf16_f32 v228, v12, v13
	v_cvt_pk_bf16_f32 v229, v14, v15
	v_cvt_pk_bf16_f32 v230, v8, v9
	v_cvt_pk_bf16_f32 v231, v10, v11
	v_cvt_pk_bf16_f32 v232, v4, v5
	v_cvt_pk_bf16_f32 v233, v6, v7
	v_cvt_pk_bf16_f32 v234, v0, v1
	v_cvt_pk_bf16_f32 v235, v2, v3
	v_add_u32_e32 v172, 0xb0, v174
	v_mov_b32_e32 v173, 0
	v_lshlrev_b64 v[250:251], 12, v[172:173]
	v_lshl_add_u64 v[250:251], v[248:249], 0, v[250:251]
	v_mov_b32_dpp v236, v232 row_ror:8 row_mask:0xf bank_mask:0xf bound_ctrl:1
	v_mov_b32_dpp v237, v233 row_ror:8 row_mask:0xf bank_mask:0xf bound_ctrl:1
	v_mov_b32_dpp v238, v234 row_ror:8 row_mask:0xf bank_mask:0xf bound_ctrl:1
	v_mov_b32_dpp v239, v235 row_ror:8 row_mask:0xf bank_mask:0xf bound_ctrl:1
	v_cndmask_b32_e64 v240, v236, v228, s[18:19]
	v_cndmask_b32_e64 v241, v237, v229, s[18:19]
	v_cndmask_b32_e64 v242, v238, v230, s[18:19]
	v_cndmask_b32_e64 v243, v239, v231, s[18:19]
	global_store_dwordx4 v[250:251], v[240:243], off sc1
	s_nop 1
	v_mov_b32_dpp v236, v228 row_ror:8 row_mask:0xf bank_mask:0xf bound_ctrl:1
	v_mov_b32_dpp v237, v229 row_ror:8 row_mask:0xf bank_mask:0xf bound_ctrl:1
	v_mov_b32_dpp v238, v230 row_ror:8 row_mask:0xf bank_mask:0xf bound_ctrl:1
	v_mov_b32_dpp v239, v231 row_ror:8 row_mask:0xf bank_mask:0xf bound_ctrl:1
	v_cndmask_b32_e64 v244, v232, v236, s[18:19]
	v_cndmask_b32_e64 v245, v233, v237, s[18:19]
	v_cndmask_b32_e64 v246, v234, v238, s[18:19]
	v_cndmask_b32_e64 v247, v235, v239, s[18:19]
	v_lshl_add_u64 v[250:251], v[250:251], 0, s[88:89]
	global_store_dwordx4 v[250:251], v[244:247], off sc1
	s_nop 1
.Lxd20_h:
	ds_read_b128 v[104:107], v209
	ds_read_b128 v[108:111], v210
	ds_read_b128 v[112:115], v209 offset:16
	ds_read_b128 v[116:119], v210 offset:16
	ds_read_b128 v[120:123], v209 offset:128
	ds_read_b128 v[124:127], v210 offset:128
	ds_read_b128 v[192:195], v209 offset:144
	ds_read_b128 v[196:199], v210 offset:144
	v_cmp_eq_u32_e64 s[24:25], 0, v66
	v_mov_b32_e32 v102, 0x7fc00000
	v_add_u32_e32 v152, v178, v207
	v_ashrrev_i32_e32 v153, 31, v152
	v_lshlrev_b64 v[152:153], 1, v[152:153]
	v_lshl_add_u64 v[144:145], s[86:87], 0, v[152:153]
	v_or_b32_e32 v154, s41, v208
	s_mov_b32 s88, 0x4000
	s_mov_b32 s89, 0
	ds_read_b32 v100, v211
	v_add_u32_e32 v152, 0, v154
	v_mov_b32_e32 v153, 0
	v_lshlrev_b64 v[146:147], 11, v[152:153]
	v_lshl_add_u64 v[146:147], v[144:145], 0, v[146:147]
	s_waitcnt lgkmcnt(0)
	v_cndmask_b32_e64 v100, v102, v100, s[24:25]
	v_pk_mul_f32 v[228:229], v[140:141], v[100:101] op_sel_hi:[1,0]
	v_pk_mul_f32 v[230:231], v[142:143], v[100:101] op_sel_hi:[1,0]
	v_pk_mul_f32 v[232:233], v[136:137], v[100:101] op_sel_hi:[1,0]
	v_pk_mul_f32 v[234:235], v[138:139], v[100:101] op_sel_hi:[1,0]
	v_pk_mul_f32 v[236:237], v[132:133], v[100:101] op_sel_hi:[1,0]
	v_pk_mul_f32 v[238:239], v[134:135], v[100:101] op_sel_hi:[1,0]
	v_pk_mul_f32 v[240:241], v[180:181], v[100:101] op_sel_hi:[1,0]
	v_pk_mul_f32 v[242:243], v[168:169], v[100:101] op_sel_hi:[1,0]
	v_pk_fma_f32 v[228:229], v[104:105], v[228:229], v[108:109]
	v_pk_fma_f32 v[230:231], v[106:107], v[230:231], v[110:111]
	v_pk_fma_f32 v[232:233], v[112:113], v[232:233], v[116:117]
	v_pk_fma_f32 v[234:235], v[114:115], v[234:235], v[118:119]
	v_pk_fma_f32 v[236:237], v[120:121], v[236:237], v[124:125]
	v_pk_fma_f32 v[238:239], v[122:123], v[238:239], v[126:127]
	v_pk_fma_f32 v[240:241], v[192:193], v[240:241], v[196:197]
	v_pk_fma_f32 v[242:243], v[194:195], v[242:243], v[198:199]
	v_cvt_pk_bf16_f32 v244, v228, v229
	v_cvt_pk_bf16_f32 v245, v230, v231
	v_cvt_pk_bf16_f32 v246, v232, v233
	v_cvt_pk_bf16_f32 v247, v234, v235
	v_cvt_pk_bf16_f32 v248, v236, v237
	v_cvt_pk_bf16_f32 v249, v238, v239
	v_cvt_pk_bf16_f32 v250, v240, v241
	v_cvt_pk_bf16_f32 v251, v242, v243
	v_mov_b32_dpp v72, v248 row_ror:8 row_mask:0xf bank_mask:0xf bound_ctrl:1
	v_mov_b32_dpp v73, v249 row_ror:8 row_mask:0xf bank_mask:0xf bound_ctrl:1
	v_mov_b32_dpp v74, v250 row_ror:8 row_mask:0xf bank_mask:0xf bound_ctrl:1
	v_mov_b32_dpp v75, v251 row_ror:8 row_mask:0xf bank_mask:0xf bound_ctrl:1
	v_cndmask_b32_e64 v76, v72, v244, s[18:19]
	v_cndmask_b32_e64 v77, v73, v245, s[18:19]
	v_cndmask_b32_e64 v78, v74, v246, s[18:19]
	v_cndmask_b32_e64 v79, v75, v247, s[18:19]
	global_store_dwordx4 v[146:147], v[76:79], off sc1
	s_nop 1
	v_mov_b32_dpp v72, v244 row_ror:8 row_mask:0xf bank_mask:0xf bound_ctrl:1
	v_mov_b32_dpp v73, v245 row_ror:8 row_mask:0xf bank_mask:0xf bound_ctrl:1
	v_mov_b32_dpp v74, v246 row_ror:8 row_mask:0xf bank_mask:0xf bound_ctrl:1
	v_mov_b32_dpp v75, v247 row_ror:8 row_mask:0xf bank_mask:0xf bound_ctrl:1
	v_cndmask_b32_e64 v96, v248, v72, s[18:19]
	v_cndmask_b32_e64 v97, v249, v73, s[18:19]
	v_cndmask_b32_e64 v98, v250, v74, s[18:19]
	v_cndmask_b32_e64 v99, v251, v75, s[18:19]
	v_lshl_add_u64 v[146:147], v[146:147], 0, s[88:89]
	global_store_dwordx4 v[146:147], v[96:99], off sc1
	s_nop 1
	ds_read_b32 v100, v211 offset:64
	v_add_u32_e32 v152, 16, v154
	v_mov_b32_e32 v153, 0
	v_lshlrev_b64 v[146:147], 11, v[152:153]
	v_lshl_add_u64 v[146:147], v[144:145], 0, v[146:147]
	s_waitcnt lgkmcnt(0)
; #define LAS __attribute__((address_space(3)))
; __device__ __forceinline__ unsigned cvt_pk_bf16(float lo, float hi) { const f32x2 v = {lo, hi}; const bf16x2_t b = __builtin_convertvector(v, bf16x2_t); return __builtin_bit_cast(unsigned, b); }
; __device__ __forceinline__ void store16_wt(void* p, u32x4 v) { asm volatile("global_store_dwordx4 %0, %1, off sc1\n\ts_nop 1" :: "v"(p), "v"(v) : "memory"); }
; __device__ __forceinline__ u32x4 ror8_u4(u32x4 v) { const unsigned a = ror8_u(v.x), b = ror8_u(v.y), c = ror8_u(v.z), d = ror8_u(v.w); return (u32x4){a, b, c, d}; }
;     __device__ __forceinline__ void epi(AccT& acc, const Unit& u, LAS unsigned char* lds, int wr, int wc, int fr, int fq) const {
;     ...
;                 for (int m = 0; m < 4; ++m) { const int r = ai * 128 + wr * 64 + m * 16 + fr; const float rs = bad ? qnan : Sl[r];
;                     const size_t rowA = (size_t)(u.pm * 256 + ai * 128 + wr * 64 + m * 16 + (fr & 7)); u32x4 p[2], q[2];
; #pragma unroll
;                     for (int bj = 0; bj < 2; ++bj) { const f32x4 x0 = acc[ai][bj][m][0], x1 = acc[ai][bj][m][1];
;                         const f32x4 h0 = x0 * rs * *(const LAS f32x4*)(svl + cl + bj * 32) + *(const LAS f32x4*)(tvl + cl + bj * 32), h1 = x1 * rs * *(const LAS f32x4*)(svl + cl + bj * 32 + 4) + *(const LAS f32x4*)(tvl + cl + bj * 32 + 4);
;                         p[bj].x = cvt_pk_bf16(h0[0], h0[1]); p[bj].y = cvt_pk_bf16(h0[2], h0[3]); p[bj].z = cvt_pk_bf16(h1[0], h1[1]); p[bj].w = cvt_pk_bf16(h1[2], h1[3]);
;                         q[bj].x = cvt_pk_bf16(x0[0], x0[1]); q[bj].y = cvt_pk_bf16(x0[2], x0[3]); q[bj].z = cvt_pk_bf16(x1[0], x1[1]); q[bj].w = cvt_pk_bf16(x1[2], x1[3]); }
;                     const u32x4 rq0 = ror8_u4(q[0]), rq1 = ror8_u4(q[1]), rp0 = ror8_u4(p[0]), rp1 = ror8_u4(p[1]);
;                     store16_wt(XHw + rowA * (2 * D) + colp, lo ? q[0] : rq1); store16_wt(XHw + (rowA + 8) * (2 * D) + colp, lo ? rq0 : q[1]);
;                     store16_wt(H + rowA * D + colp, lo ? p[0] : rp1); store16_wt(H + (rowA + 8) * D + colp, lo ? rp0 : p[1]); }
	v_cndmask_b32_e64 v100, v102, v100, s[24:25]
	v_pk_mul_f32 v[228:229], v[170:171], v[100:101] op_sel_hi:[1,0]
	v_pk_mul_f32 v[230:231], v[164:165], v[100:101] op_sel_hi:[1,0]
	v_pk_mul_f32 v[232:233], v[188:189], v[100:101] op_sel_hi:[1,0]
	v_pk_mul_f32 v[234:235], v[184:185], v[100:101] op_sel_hi:[1,0]
	v_pk_mul_f32 v[236:237], v[182:183], v[100:101] op_sel_hi:[1,0]
	v_pk_mul_f32 v[238:239], v[166:167], v[100:101] op_sel_hi:[1,0]
	v_pk_mul_f32 v[240:241], v[190:191], v[100:101] op_sel_hi:[1,0]
	v_pk_mul_f32 v[242:243], v[186:187], v[100:101] op_sel_hi:[1,0]
	v_pk_fma_f32 v[228:229], v[104:105], v[228:229], v[108:109]
	v_pk_fma_f32 v[230:231], v[106:107], v[230:231], v[110:111]
	v_pk_fma_f32 v[232:233], v[112:113], v[232:233], v[116:117]
	v_pk_fma_f32 v[234:235], v[114:115], v[234:235], v[118:119]
	v_pk_fma_f32 v[236:237], v[120:121], v[236:237], v[124:125]
	v_pk_fma_f32 v[238:239], v[122:123], v[238:239], v[126:127]
	v_pk_fma_f32 v[240:241], v[192:193], v[240:241], v[196:197]
	v_pk_fma_f32 v[242:243], v[194:195], v[242:243], v[198:199]
	v_cvt_pk_bf16_f32 v244, v228, v229
	v_cvt_pk_bf16_f32 v245, v230, v231
	v_cvt_pk_bf16_f32 v246, v232, v233
	v_cvt_pk_bf16_f32 v247, v234, v235
	v_cvt_pk_bf16_f32 v248, v236, v237
	v_cvt_pk_bf16_f32 v249, v238, v239
	v_cvt_pk_bf16_f32 v250, v240, v241
	v_cvt_pk_bf16_f32 v251, v242, v243
	v_mov_b32_dpp v72, v248 row_ror:8 row_mask:0xf bank_mask:0xf bound_ctrl:1
	v_mov_b32_dpp v73, v249 row_ror:8 row_mask:0xf bank_mask:0xf bound_ctrl:1
	v_mov_b32_dpp v74, v250 row_ror:8 row_mask:0xf bank_mask:0xf bound_ctrl:1
	v_mov_b32_dpp v75, v251 row_ror:8 row_mask:0xf bank_mask:0xf bound_ctrl:1
	v_cndmask_b32_e64 v76, v72, v244, s[18:19]
	v_cndmask_b32_e64 v77, v73, v245, s[18:19]
	v_cndmask_b32_e64 v78, v74, v246, s[18:19]
	v_cndmask_b32_e64 v79, v75, v247, s[18:19]
	global_store_dwordx4 v[146:147], v[76:79], off sc1
	s_nop 1
	v_mov_b32_dpp v72, v244 row_ror:8 row_mask:0xf bank_mask:0xf bound_ctrl:1
	v_mov_b32_dpp v73, v245 row_ror:8 row_mask:0xf bank_mask:0xf bound_ctrl:1
	v_mov_b32_dpp v74, v246 row_ror:8 row_mask:0xf bank_mask:0xf bound_ctrl:1
	v_mov_b32_dpp v75, v247 row_ror:8 row_mask:0xf bank_mask:0xf bound_ctrl:1
	v_cndmask_b32_e64 v96, v248, v72, s[18:19]
	v_cndmask_b32_e64 v97, v249, v73, s[18:19]
	v_cndmask_b32_e64 v98, v250, v74, s[18:19]
	v_cndmask_b32_e64 v99, v251, v75, s[18:19]
	v_lshl_add_u64 v[146:147], v[146:147], 0, s[88:89]
	global_store_dwordx4 v[146:147], v[96:99], off sc1
	s_nop 1
	ds_read_b32 v100, v211 offset:128
	v_add_u32_e32 v152, 32, v154
	v_mov_b32_e32 v153, 0
	v_lshlrev_b64 v[146:147], 11, v[152:153]
	v_lshl_add_u64 v[146:147], v[144:145], 0, v[146:147]
	s_waitcnt lgkmcnt(0)
	v_cndmask_b32_e64 v100, v102, v100, s[24:25]
	v_pk_mul_f32 v[228:229], v[130:131], v[100:101] op_sel_hi:[1,0]
	v_pk_mul_f32 v[230:231], v[128:129], v[100:101] op_sel_hi:[1,0]
	v_pk_mul_f32 v[232:233], v[160:161], v[100:101] op_sel_hi:[1,0]
	v_pk_mul_f32 v[234:235], v[158:159], v[100:101] op_sel_hi:[1,0]
	v_pk_mul_f32 v[236:237], v[156:157], v[100:101] op_sel_hi:[1,0]
	v_pk_mul_f32 v[238:239], v[148:149], v[100:101] op_sel_hi:[1,0]
	v_pk_mul_f32 v[240:241], v[162:163], v[100:101] op_sel_hi:[1,0]
	v_pk_mul_f32 v[242:243], v[150:151], v[100:101] op_sel_hi:[1,0]
	v_pk_fma_f32 v[228:229], v[104:105], v[228:229], v[108:109]
	v_pk_fma_f32 v[230:231], v[106:107], v[230:231], v[110:111]
	v_pk_fma_f32 v[232:233], v[112:113], v[232:233], v[116:117]
	v_pk_fma_f32 v[234:235], v[114:115], v[234:235], v[118:119]
	v_pk_fma_f32 v[236:237], v[120:121], v[236:237], v[124:125]
	v_pk_fma_f32 v[238:239], v[122:123], v[238:239], v[126:127]
	v_pk_fma_f32 v[240:241], v[192:193], v[240:241], v[196:197]
	v_pk_fma_f32 v[242:243], v[194:195], v[242:243], v[198:199]
	v_cvt_pk_bf16_f32 v244, v228, v229
	v_cvt_pk_bf16_f32 v245, v230, v231
	v_cvt_pk_bf16_f32 v246, v232, v233
	v_cvt_pk_bf16_f32 v247, v234, v235
	v_cvt_pk_bf16_f32 v248, v236, v237
	v_cvt_pk_bf16_f32 v249, v238, v239
	v_cvt_pk_bf16_f32 v250, v240, v241
	v_cvt_pk_bf16_f32 v251, v242, v243
	v_mov_b32_dpp v72, v248 row_ror:8 row_mask:0xf bank_mask:0xf bound_ctrl:1
	v_mov_b32_dpp v73, v249 row_ror:8 row_mask:0xf bank_mask:0xf bound_ctrl:1
	v_mov_b32_dpp v74, v250 row_ror:8 row_mask:0xf bank_mask:0xf bound_ctrl:1
	v_mov_b32_dpp v75, v251 row_ror:8 row_mask:0xf bank_mask:0xf bound_ctrl:1
	v_cndmask_b32_e64 v76, v72, v244, s[18:19]
	v_cndmask_b32_e64 v77, v73, v245, s[18:19]
	v_cndmask_b32_e64 v78, v74, v246, s[18:19]
	v_cndmask_b32_e64 v79, v75, v247, s[18:19]
	global_store_dwordx4 v[146:147], v[76:79], off sc1
	s_nop 1
	v_mov_b32_dpp v72, v244 row_ror:8 row_mask:0xf bank_mask:0xf bound_ctrl:1
	v_mov_b32_dpp v73, v245 row_ror:8 row_mask:0xf bank_mask:0xf bound_ctrl:1
	v_mov_b32_dpp v74, v246 row_ror:8 row_mask:0xf bank_mask:0xf bound_ctrl:1
	v_mov_b32_dpp v75, v247 row_ror:8 row_mask:0xf bank_mask:0xf bound_ctrl:1
	v_cndmask_b32_e64 v96, v248, v72, s[18:19]
	v_cndmask_b32_e64 v97, v249, v73, s[18:19]
	v_cndmask_b32_e64 v98, v250, v74, s[18:19]
	v_cndmask_b32_e64 v99, v251, v75, s[18:19]
	v_lshl_add_u64 v[146:147], v[146:147], 0, s[88:89]
	global_store_dwordx4 v[146:147], v[96:99], off sc1
	s_nop 1
	ds_read_b32 v100, v211 offset:192
	v_add_u32_e32 v152, 48, v154
	v_mov_b32_e32 v153, 0
	v_lshlrev_b64 v[146:147], 11, v[152:153]
	v_lshl_add_u64 v[146:147], v[144:145], 0, v[146:147]
	s_waitcnt lgkmcnt(0)
; #define LAS __attribute__((address_space(3)))
; __device__ __forceinline__ unsigned cvt_pk_bf16(float lo, float hi) { const f32x2 v = {lo, hi}; const bf16x2_t b = __builtin_convertvector(v, bf16x2_t); return __builtin_bit_cast(unsigned, b); }
; __device__ __forceinline__ void store16_wt(void* p, u32x4 v) { asm volatile("global_store_dwordx4 %0, %1, off sc1\n\ts_nop 1" :: "v"(p), "v"(v) : "memory"); }
; __device__ __forceinline__ u32x4 ror8_u4(u32x4 v) { const unsigned a = ror8_u(v.x), b = ror8_u(v.y), c = ror8_u(v.z), d = ror8_u(v.w); return (u32x4){a, b, c, d}; }
;     __device__ __forceinline__ void epi(AccT& acc, const Unit& u, LAS unsigned char* lds, int wr, int wc, int fr, int fq) const {
;     ...
;                 for (int m = 0; m < 4; ++m) { const int r = ai * 128 + wr * 64 + m * 16 + fr; const float rs = bad ? qnan : Sl[r];
;                     const size_t rowA = (size_t)(u.pm * 256 + ai * 128 + wr * 64 + m * 16 + (fr & 7)); u32x4 p[2], q[2];
; #pragma unroll
;                     for (int bj = 0; bj < 2; ++bj) { const f32x4 x0 = acc[ai][bj][m][0], x1 = acc[ai][bj][m][1];
;                         const f32x4 h0 = x0 * rs * *(const LAS f32x4*)(svl + cl + bj * 32) + *(const LAS f32x4*)(tvl + cl + bj * 32), h1 = x1 * rs * *(const LAS f32x4*)(svl + cl + bj * 32 + 4) + *(const LAS f32x4*)(tvl + cl + bj * 32 + 4);
;                         p[bj].x = cvt_pk_bf16(h0[0], h0[1]); p[bj].y = cvt_pk_bf16(h0[2], h0[3]); p[bj].z = cvt_pk_bf16(h1[0], h1[1]); p[bj].w = cvt_pk_bf16(h1[2], h1[3]);
;                         q[bj].x = cvt_pk_bf16(x0[0], x0[1]); q[bj].y = cvt_pk_bf16(x0[2], x0[3]); q[bj].z = cvt_pk_bf16(x1[0], x1[1]); q[bj].w = cvt_pk_bf16(x1[2], x1[3]); }
;                     const u32x4 rq0 = ror8_u4(q[0]), rq1 = ror8_u4(q[1]), rp0 = ror8_u4(p[0]), rp1 = ror8_u4(p[1]);
;                     store16_wt(XHw + rowA * (2 * D) + colp, lo ? q[0] : rq1); store16_wt(XHw + (rowA + 8) * (2 * D) + colp, lo ? rq0 : q[1]);
;                     store16_wt(H + rowA * D + colp, lo ? p[0] : rp1); store16_wt(H + (rowA + 8) * D + colp, lo ? rp0 : p[1]); }
	v_cndmask_b32_e64 v100, v102, v100, s[24:25]
	v_pk_mul_f32 v[228:229], v[84:85], v[100:101] op_sel_hi:[1,0]
	v_pk_mul_f32 v[230:231], v[80:81], v[100:101] op_sel_hi:[1,0]
	v_pk_mul_f32 v[232:233], v[92:93], v[100:101] op_sel_hi:[1,0]
	v_pk_mul_f32 v[234:235], v[88:89], v[100:101] op_sel_hi:[1,0]
	v_pk_mul_f32 v[236:237], v[86:87], v[100:101] op_sel_hi:[1,0]
	v_pk_mul_f32 v[238:239], v[82:83], v[100:101] op_sel_hi:[1,0]
	v_pk_mul_f32 v[240:241], v[94:95], v[100:101] op_sel_hi:[1,0]
	v_pk_mul_f32 v[242:243], v[90:91], v[100:101] op_sel_hi:[1,0]
	v_pk_fma_f32 v[228:229], v[104:105], v[228:229], v[108:109]
	v_pk_fma_f32 v[230:231], v[106:107], v[230:231], v[110:111]
	v_pk_fma_f32 v[232:233], v[112:113], v[232:233], v[116:117]
	v_pk_fma_f32 v[234:235], v[114:115], v[234:235], v[118:119]
	v_pk_fma_f32 v[236:237], v[120:121], v[236:237], v[124:125]
	v_pk_fma_f32 v[238:239], v[122:123], v[238:239], v[126:127]
	v_pk_fma_f32 v[240:241], v[192:193], v[240:241], v[196:197]
	v_pk_fma_f32 v[242:243], v[194:195], v[242:243], v[198:199]
	v_cvt_pk_bf16_f32 v244, v228, v229
	v_cvt_pk_bf16_f32 v245, v230, v231
	v_cvt_pk_bf16_f32 v246, v232, v233
	v_cvt_pk_bf16_f32 v247, v234, v235
	v_cvt_pk_bf16_f32 v248, v236, v237
	v_cvt_pk_bf16_f32 v249, v238, v239
	v_cvt_pk_bf16_f32 v250, v240, v241
	v_cvt_pk_bf16_f32 v251, v242, v243
	v_mov_b32_dpp v72, v248 row_ror:8 row_mask:0xf bank_mask:0xf bound_ctrl:1
	v_mov_b32_dpp v73, v249 row_ror:8 row_mask:0xf bank_mask:0xf bound_ctrl:1
	v_mov_b32_dpp v74, v250 row_ror:8 row_mask:0xf bank_mask:0xf bound_ctrl:1
	v_mov_b32_dpp v75, v251 row_ror:8 row_mask:0xf bank_mask:0xf bound_ctrl:1
	v_cndmask_b32_e64 v76, v72, v244, s[18:19]
	v_cndmask_b32_e64 v77, v73, v245, s[18:19]
	v_cndmask_b32_e64 v78, v74, v246, s[18:19]
	v_cndmask_b32_e64 v79, v75, v247, s[18:19]
	global_store_dwordx4 v[146:147], v[76:79], off sc1
	s_nop 1
	v_mov_b32_dpp v72, v244 row_ror:8 row_mask:0xf bank_mask:0xf bound_ctrl:1
	v_mov_b32_dpp v73, v245 row_ror:8 row_mask:0xf bank_mask:0xf bound_ctrl:1
	v_mov_b32_dpp v74, v246 row_ror:8 row_mask:0xf bank_mask:0xf bound_ctrl:1
	v_mov_b32_dpp v75, v247 row_ror:8 row_mask:0xf bank_mask:0xf bound_ctrl:1
	v_cndmask_b32_e64 v96, v248, v72, s[18:19]
	v_cndmask_b32_e64 v97, v249, v73, s[18:19]
	v_cndmask_b32_e64 v98, v250, v74, s[18:19]
	v_cndmask_b32_e64 v99, v251, v75, s[18:19]
	v_lshl_add_u64 v[146:147], v[146:147], 0, s[88:89]
	global_store_dwordx4 v[146:147], v[96:99], off sc1
	s_nop 1
	ds_read_b32 v100, v211 offset:512
	v_add_u32_e32 v152, 0x80, v154
	v_mov_b32_e32 v153, 0
	v_lshlrev_b64 v[146:147], 11, v[152:153]
	v_lshl_add_u64 v[146:147], v[144:145], 0, v[146:147]
	s_waitcnt lgkmcnt(0)
	v_cndmask_b32_e64 v100, v102, v100, s[24:25]
	v_pk_mul_f32 v[228:229], v[60:61], v[100:101] op_sel_hi:[1,0]
	v_pk_mul_f32 v[230:231], v[62:63], v[100:101] op_sel_hi:[1,0]
	v_pk_mul_f32 v[232:233], v[56:57], v[100:101] op_sel_hi:[1,0]
	v_pk_mul_f32 v[234:235], v[58:59], v[100:101] op_sel_hi:[1,0]
	v_pk_mul_f32 v[236:237], v[52:53], v[100:101] op_sel_hi:[1,0]
	v_pk_mul_f32 v[238:239], v[54:55], v[100:101] op_sel_hi:[1,0]
	v_pk_mul_f32 v[240:241], v[48:49], v[100:101] op_sel_hi:[1,0]
	v_pk_mul_f32 v[242:243], v[50:51], v[100:101] op_sel_hi:[1,0]
	v_pk_fma_f32 v[228:229], v[104:105], v[228:229], v[108:109]
	v_pk_fma_f32 v[230:231], v[106:107], v[230:231], v[110:111]
	v_pk_fma_f32 v[232:233], v[112:113], v[232:233], v[116:117]
	v_pk_fma_f32 v[234:235], v[114:115], v[234:235], v[118:119]
	v_pk_fma_f32 v[236:237], v[120:121], v[236:237], v[124:125]
	v_pk_fma_f32 v[238:239], v[122:123], v[238:239], v[126:127]
	v_pk_fma_f32 v[240:241], v[192:193], v[240:241], v[196:197]
	v_pk_fma_f32 v[242:243], v[194:195], v[242:243], v[198:199]
	v_cvt_pk_bf16_f32 v244, v228, v229
	v_cvt_pk_bf16_f32 v245, v230, v231
	v_cvt_pk_bf16_f32 v246, v232, v233
	v_cvt_pk_bf16_f32 v247, v234, v235
	v_cvt_pk_bf16_f32 v248, v236, v237
	v_cvt_pk_bf16_f32 v249, v238, v239
	v_cvt_pk_bf16_f32 v250, v240, v241
	v_cvt_pk_bf16_f32 v251, v242, v243
	v_mov_b32_dpp v72, v248 row_ror:8 row_mask:0xf bank_mask:0xf bound_ctrl:1
	v_mov_b32_dpp v73, v249 row_ror:8 row_mask:0xf bank_mask:0xf bound_ctrl:1
	v_mov_b32_dpp v74, v250 row_ror:8 row_mask:0xf bank_mask:0xf bound_ctrl:1
	v_mov_b32_dpp v75, v251 row_ror:8 row_mask:0xf bank_mask:0xf bound_ctrl:1
	v_cndmask_b32_e64 v76, v72, v244, s[18:19]
	v_cndmask_b32_e64 v77, v73, v245, s[18:19]
	v_cndmask_b32_e64 v78, v74, v246, s[18:19]
	v_cndmask_b32_e64 v79, v75, v247, s[18:19]
	global_store_dwordx4 v[146:147], v[76:79], off sc1
	s_nop 1
	v_mov_b32_dpp v72, v244 row_ror:8 row_mask:0xf bank_mask:0xf bound_ctrl:1
	v_mov_b32_dpp v73, v245 row_ror:8 row_mask:0xf bank_mask:0xf bound_ctrl:1
	v_mov_b32_dpp v74, v246 row_ror:8 row_mask:0xf bank_mask:0xf bound_ctrl:1
	v_mov_b32_dpp v75, v247 row_ror:8 row_mask:0xf bank_mask:0xf bound_ctrl:1
	v_cndmask_b32_e64 v96, v248, v72, s[18:19]
	v_cndmask_b32_e64 v97, v249, v73, s[18:19]
	v_cndmask_b32_e64 v98, v250, v74, s[18:19]
	v_cndmask_b32_e64 v99, v251, v75, s[18:19]
	v_lshl_add_u64 v[146:147], v[146:147], 0, s[88:89]
	global_store_dwordx4 v[146:147], v[96:99], off sc1
	s_nop 1
	ds_read_b32 v100, v211 offset:576
	v_add_u32_e32 v152, 0x90, v154
	v_mov_b32_e32 v153, 0
	v_lshlrev_b64 v[146:147], 11, v[152:153]
	v_lshl_add_u64 v[146:147], v[144:145], 0, v[146:147]
	s_waitcnt lgkmcnt(0)
; #define LAS __attribute__((address_space(3)))
; __device__ __forceinline__ unsigned cvt_pk_bf16(float lo, float hi) { const f32x2 v = {lo, hi}; const bf16x2_t b = __builtin_convertvector(v, bf16x2_t); return __builtin_bit_cast(unsigned, b); }
; __device__ __forceinline__ void store16_wt(void* p, u32x4 v) { asm volatile("global_store_dwordx4 %0, %1, off sc1\n\ts_nop 1" :: "v"(p), "v"(v) : "memory"); }
; __device__ __forceinline__ u32x4 ror8_u4(u32x4 v) { const unsigned a = ror8_u(v.x), b = ror8_u(v.y), c = ror8_u(v.z), d = ror8_u(v.w); return (u32x4){a, b, c, d}; }
;     __device__ __forceinline__ void epi(AccT& acc, const Unit& u, LAS unsigned char* lds, int wr, int wc, int fr, int fq) const {
;     ...
;                 for (int m = 0; m < 4; ++m) { const int r = ai * 128 + wr * 64 + m * 16 + fr; const float rs = bad ? qnan : Sl[r];
;                     const size_t rowA = (size_t)(u.pm * 256 + ai * 128 + wr * 64 + m * 16 + (fr & 7)); u32x4 p[2], q[2];
; #pragma unroll
;                     for (int bj = 0; bj < 2; ++bj) { const f32x4 x0 = acc[ai][bj][m][0], x1 = acc[ai][bj][m][1];
;                         const f32x4 h0 = x0 * rs * *(const LAS f32x4*)(svl + cl + bj * 32) + *(const LAS f32x4*)(tvl + cl + bj * 32), h1 = x1 * rs * *(const LAS f32x4*)(svl + cl + bj * 32 + 4) + *(const LAS f32x4*)(tvl + cl + bj * 32 + 4);
;                         p[bj].x = cvt_pk_bf16(h0[0], h0[1]); p[bj].y = cvt_pk_bf16(h0[2], h0[3]); p[bj].z = cvt_pk_bf16(h1[0], h1[1]); p[bj].w = cvt_pk_bf16(h1[2], h1[3]);
;                         q[bj].x = cvt_pk_bf16(x0[0], x0[1]); q[bj].y = cvt_pk_bf16(x0[2], x0[3]); q[bj].z = cvt_pk_bf16(x1[0], x1[1]); q[bj].w = cvt_pk_bf16(x1[2], x1[3]); }
;                     const u32x4 rq0 = ror8_u4(q[0]), rq1 = ror8_u4(q[1]), rp0 = ror8_u4(p[0]), rp1 = ror8_u4(p[1]);
;                     store16_wt(XHw + rowA * (2 * D) + colp, lo ? q[0] : rq1); store16_wt(XHw + (rowA + 8) * (2 * D) + colp, lo ? rq0 : q[1]);
;                     store16_wt(H + rowA * D + colp, lo ? p[0] : rp1); store16_wt(H + (rowA + 8) * D + colp, lo ? rp0 : p[1]); }
	v_cndmask_b32_e64 v100, v102, v100, s[24:25]
	v_pk_mul_f32 v[228:229], v[44:45], v[100:101] op_sel_hi:[1,0]
	v_pk_mul_f32 v[230:231], v[46:47], v[100:101] op_sel_hi:[1,0]
	v_pk_mul_f32 v[232:233], v[40:41], v[100:101] op_sel_hi:[1,0]
	v_pk_mul_f32 v[234:235], v[42:43], v[100:101] op_sel_hi:[1,0]
	v_pk_mul_f32 v[236:237], v[36:37], v[100:101] op_sel_hi:[1,0]
	v_pk_mul_f32 v[238:239], v[38:39], v[100:101] op_sel_hi:[1,0]
	v_pk_mul_f32 v[240:241], v[32:33], v[100:101] op_sel_hi:[1,0]
	v_pk_mul_f32 v[242:243], v[34:35], v[100:101] op_sel_hi:[1,0]
	v_pk_fma_f32 v[228:229], v[104:105], v[228:229], v[108:109]
	v_pk_fma_f32 v[230:231], v[106:107], v[230:231], v[110:111]
	v_pk_fma_f32 v[232:233], v[112:113], v[232:233], v[116:117]
	v_pk_fma_f32 v[234:235], v[114:115], v[234:235], v[118:119]
	v_pk_fma_f32 v[236:237], v[120:121], v[236:237], v[124:125]
	v_pk_fma_f32 v[238:239], v[122:123], v[238:239], v[126:127]
	v_pk_fma_f32 v[240:241], v[192:193], v[240:241], v[196:197]
	v_pk_fma_f32 v[242:243], v[194:195], v[242:243], v[198:199]
	v_cvt_pk_bf16_f32 v244, v228, v229
	v_cvt_pk_bf16_f32 v245, v230, v231
	v_cvt_pk_bf16_f32 v246, v232, v233
	v_cvt_pk_bf16_f32 v247, v234, v235
	v_cvt_pk_bf16_f32 v248, v236, v237
	v_cvt_pk_bf16_f32 v249, v238, v239
	v_cvt_pk_bf16_f32 v250, v240, v241
	v_cvt_pk_bf16_f32 v251, v242, v243
	v_mov_b32_dpp v72, v248 row_ror:8 row_mask:0xf bank_mask:0xf bound_ctrl:1
	v_mov_b32_dpp v73, v249 row_ror:8 row_mask:0xf bank_mask:0xf bound_ctrl:1
	v_mov_b32_dpp v74, v250 row_ror:8 row_mask:0xf bank_mask:0xf bound_ctrl:1
	v_mov_b32_dpp v75, v251 row_ror:8 row_mask:0xf bank_mask:0xf bound_ctrl:1
	v_cndmask_b32_e64 v76, v72, v244, s[18:19]
	v_cndmask_b32_e64 v77, v73, v245, s[18:19]
	v_cndmask_b32_e64 v78, v74, v246, s[18:19]
	v_cndmask_b32_e64 v79, v75, v247, s[18:19]
	global_store_dwordx4 v[146:147], v[76:79], off sc1
	s_nop 1
	v_mov_b32_dpp v72, v244 row_ror:8 row_mask:0xf bank_mask:0xf bound_ctrl:1
	v_mov_b32_dpp v73, v245 row_ror:8 row_mask:0xf bank_mask:0xf bound_ctrl:1
	v_mov_b32_dpp v74, v246 row_ror:8 row_mask:0xf bank_mask:0xf bound_ctrl:1
	v_mov_b32_dpp v75, v247 row_ror:8 row_mask:0xf bank_mask:0xf bound_ctrl:1
	v_cndmask_b32_e64 v96, v248, v72, s[18:19]
	v_cndmask_b32_e64 v97, v249, v73, s[18:19]
	v_cndmask_b32_e64 v98, v250, v74, s[18:19]
	v_cndmask_b32_e64 v99, v251, v75, s[18:19]
	v_lshl_add_u64 v[146:147], v[146:147], 0, s[88:89]
	global_store_dwordx4 v[146:147], v[96:99], off sc1
	s_nop 1
	ds_read_b32 v100, v211 offset:640
	v_add_u32_e32 v152, 0xa0, v154
	v_mov_b32_e32 v153, 0
	v_lshlrev_b64 v[146:147], 11, v[152:153]
	v_lshl_add_u64 v[146:147], v[144:145], 0, v[146:147]
	s_waitcnt lgkmcnt(0)
	v_cndmask_b32_e64 v100, v102, v100, s[24:25]
	v_pk_mul_f32 v[228:229], v[28:29], v[100:101] op_sel_hi:[1,0]
	v_pk_mul_f32 v[230:231], v[30:31], v[100:101] op_sel_hi:[1,0]
	v_pk_mul_f32 v[232:233], v[24:25], v[100:101] op_sel_hi:[1,0]
	v_pk_mul_f32 v[234:235], v[26:27], v[100:101] op_sel_hi:[1,0]
	v_pk_mul_f32 v[236:237], v[20:21], v[100:101] op_sel_hi:[1,0]
	v_pk_mul_f32 v[238:239], v[22:23], v[100:101] op_sel_hi:[1,0]
	v_pk_mul_f32 v[240:241], v[16:17], v[100:101] op_sel_hi:[1,0]
	v_pk_mul_f32 v[242:243], v[18:19], v[100:101] op_sel_hi:[1,0]
	v_pk_fma_f32 v[228:229], v[104:105], v[228:229], v[108:109]
	v_pk_fma_f32 v[230:231], v[106:107], v[230:231], v[110:111]
	v_pk_fma_f32 v[232:233], v[112:113], v[232:233], v[116:117]
	v_pk_fma_f32 v[234:235], v[114:115], v[234:235], v[118:119]
	v_pk_fma_f32 v[236:237], v[120:121], v[236:237], v[124:125]
	v_pk_fma_f32 v[238:239], v[122:123], v[238:239], v[126:127]
	v_pk_fma_f32 v[240:241], v[192:193], v[240:241], v[196:197]
	v_pk_fma_f32 v[242:243], v[194:195], v[242:243], v[198:199]
	v_cvt_pk_bf16_f32 v244, v228, v229
	v_cvt_pk_bf16_f32 v245, v230, v231
	v_cvt_pk_bf16_f32 v246, v232, v233
	v_cvt_pk_bf16_f32 v247, v234, v235
	v_cvt_pk_bf16_f32 v248, v236, v237
	v_cvt_pk_bf16_f32 v249, v238, v239
	v_cvt_pk_bf16_f32 v250, v240, v241
	v_cvt_pk_bf16_f32 v251, v242, v243
	v_mov_b32_dpp v72, v248 row_ror:8 row_mask:0xf bank_mask:0xf bound_ctrl:1
	v_mov_b32_dpp v73, v249 row_ror:8 row_mask:0xf bank_mask:0xf bound_ctrl:1
	v_mov_b32_dpp v74, v250 row_ror:8 row_mask:0xf bank_mask:0xf bound_ctrl:1
	v_mov_b32_dpp v75, v251 row_ror:8 row_mask:0xf bank_mask:0xf bound_ctrl:1
	v_cndmask_b32_e64 v76, v72, v244, s[18:19]
	v_cndmask_b32_e64 v77, v73, v245, s[18:19]
	v_cndmask_b32_e64 v78, v74, v246, s[18:19]
	v_cndmask_b32_e64 v79, v75, v247, s[18:19]
	global_store_dwordx4 v[146:147], v[76:79], off sc1
	s_nop 1
	v_mov_b32_dpp v72, v244 row_ror:8 row_mask:0xf bank_mask:0xf bound_ctrl:1
	v_mov_b32_dpp v73, v245 row_ror:8 row_mask:0xf bank_mask:0xf bound_ctrl:1
	v_mov_b32_dpp v74, v246 row_ror:8 row_mask:0xf bank_mask:0xf bound_ctrl:1
	v_mov_b32_dpp v75, v247 row_ror:8 row_mask:0xf bank_mask:0xf bound_ctrl:1
	v_cndmask_b32_e64 v96, v248, v72, s[18:19]
	v_cndmask_b32_e64 v97, v249, v73, s[18:19]
	v_cndmask_b32_e64 v98, v250, v74, s[18:19]
	v_cndmask_b32_e64 v99, v251, v75, s[18:19]
	v_lshl_add_u64 v[146:147], v[146:147], 0, s[88:89]
	global_store_dwordx4 v[146:147], v[96:99], off sc1
	s_nop 1
	ds_read_b32 v100, v211 offset:704
	v_add_u32_e32 v152, 0xb0, v154
	v_mov_b32_e32 v153, 0
	v_lshlrev_b64 v[146:147], 11, v[152:153]
	v_lshl_add_u64 v[146:147], v[144:145], 0, v[146:147]
	s_waitcnt lgkmcnt(0)
; #define LAS __attribute__((address_space(3)))
; __device__ __forceinline__ unsigned cvt_pk_bf16(float lo, float hi) { const f32x2 v = {lo, hi}; const bf16x2_t b = __builtin_convertvector(v, bf16x2_t); return __builtin_bit_cast(unsigned, b); }
; __device__ __forceinline__ void store16_wt(void* p, u32x4 v) { asm volatile("global_store_dwordx4 %0, %1, off sc1\n\ts_nop 1" :: "v"(p), "v"(v) : "memory"); }
; __device__ __forceinline__ u32x4 ror8_u4(u32x4 v) { const unsigned a = ror8_u(v.x), b = ror8_u(v.y), c = ror8_u(v.z), d = ror8_u(v.w); return (u32x4){a, b, c, d}; }
;     __device__ __forceinline__ void epi(AccT& acc, const Unit& u, LAS unsigned char* lds, int wr, int wc, int fr, int fq) const {
;     ...
;                 for (int m = 0; m < 4; ++m) { const int r = ai * 128 + wr * 64 + m * 16 + fr; const float rs = bad ? qnan : Sl[r];
;                     const size_t rowA = (size_t)(u.pm * 256 + ai * 128 + wr * 64 + m * 16 + (fr & 7)); u32x4 p[2], q[2];
; #pragma unroll
;                     for (int bj = 0; bj < 2; ++bj) { const f32x4 x0 = acc[ai][bj][m][0], x1 = acc[ai][bj][m][1];
;                         const f32x4 h0 = x0 * rs * *(const LAS f32x4*)(svl + cl + bj * 32) + *(const LAS f32x4*)(tvl + cl + bj * 32), h1 = x1 * rs * *(const LAS f32x4*)(svl + cl + bj * 32 + 4) + *(const LAS f32x4*)(tvl + cl + bj * 32 + 4);
;                         p[bj].x = cvt_pk_bf16(h0[0], h0[1]); p[bj].y = cvt_pk_bf16(h0[2], h0[3]); p[bj].z = cvt_pk_bf16(h1[0], h1[1]); p[bj].w = cvt_pk_bf16(h1[2], h1[3]);
;                         q[bj].x = cvt_pk_bf16(x0[0], x0[1]); q[bj].y = cvt_pk_bf16(x0[2], x0[3]); q[bj].z = cvt_pk_bf16(x1[0], x1[1]); q[bj].w = cvt_pk_bf16(x1[2], x1[3]); }
;                     const u32x4 rq0 = ror8_u4(q[0]), rq1 = ror8_u4(q[1]), rp0 = ror8_u4(p[0]), rp1 = ror8_u4(p[1]);
;                     store16_wt(XHw + rowA * (2 * D) + colp, lo ? q[0] : rq1); store16_wt(XHw + (rowA + 8) * (2 * D) + colp, lo ? rq0 : q[1]);
;                     store16_wt(H + rowA * D + colp, lo ? p[0] : rp1); store16_wt(H + (rowA + 8) * D + colp, lo ? rp0 : p[1]); }
	v_cndmask_b32_e64 v100, v102, v100, s[24:25]
	v_pk_mul_f32 v[228:229], v[12:13], v[100:101] op_sel_hi:[1,0]
	v_pk_mul_f32 v[230:231], v[14:15], v[100:101] op_sel_hi:[1,0]
	v_pk_mul_f32 v[232:233], v[8:9], v[100:101] op_sel_hi:[1,0]
	v_pk_mul_f32 v[234:235], v[10:11], v[100:101] op_sel_hi:[1,0]
	v_pk_mul_f32 v[236:237], v[4:5], v[100:101] op_sel_hi:[1,0]
	v_pk_mul_f32 v[238:239], v[6:7], v[100:101] op_sel_hi:[1,0]
	v_pk_mul_f32 v[240:241], v[0:1], v[100:101] op_sel_hi:[1,0]
	v_pk_mul_f32 v[242:243], v[2:3], v[100:101] op_sel_hi:[1,0]
	v_pk_fma_f32 v[228:229], v[104:105], v[228:229], v[108:109]
	v_pk_fma_f32 v[230:231], v[106:107], v[230:231], v[110:111]
	v_pk_fma_f32 v[232:233], v[112:113], v[232:233], v[116:117]
	v_pk_fma_f32 v[234:235], v[114:115], v[234:235], v[118:119]
	v_pk_fma_f32 v[236:237], v[120:121], v[236:237], v[124:125]
	v_pk_fma_f32 v[238:239], v[122:123], v[238:239], v[126:127]
	v_pk_fma_f32 v[240:241], v[192:193], v[240:241], v[196:197]
	v_pk_fma_f32 v[242:243], v[194:195], v[242:243], v[198:199]
	v_cvt_pk_bf16_f32 v244, v228, v229
	v_cvt_pk_bf16_f32 v245, v230, v231
	v_cvt_pk_bf16_f32 v246, v232, v233
	v_cvt_pk_bf16_f32 v247, v234, v235
	v_cvt_pk_bf16_f32 v248, v236, v237
	v_cvt_pk_bf16_f32 v249, v238, v239
	v_cvt_pk_bf16_f32 v250, v240, v241
	v_cvt_pk_bf16_f32 v251, v242, v243
	v_mov_b32_dpp v72, v248 row_ror:8 row_mask:0xf bank_mask:0xf bound_ctrl:1
	v_mov_b32_dpp v73, v249 row_ror:8 row_mask:0xf bank_mask:0xf bound_ctrl:1
	v_mov_b32_dpp v74, v250 row_ror:8 row_mask:0xf bank_mask:0xf bound_ctrl:1
	v_mov_b32_dpp v75, v251 row_ror:8 row_mask:0xf bank_mask:0xf bound_ctrl:1
	v_cndmask_b32_e64 v76, v72, v244, s[18:19]
	v_cndmask_b32_e64 v77, v73, v245, s[18:19]
	v_cndmask_b32_e64 v78, v74, v246, s[18:19]
	v_cndmask_b32_e64 v79, v75, v247, s[18:19]
	global_store_dwordx4 v[146:147], v[76:79], off sc1
	s_nop 1
	v_mov_b32_dpp v72, v244 row_ror:8 row_mask:0xf bank_mask:0xf bound_ctrl:1
	v_mov_b32_dpp v73, v245 row_ror:8 row_mask:0xf bank_mask:0xf bound_ctrl:1
	v_mov_b32_dpp v74, v246 row_ror:8 row_mask:0xf bank_mask:0xf bound_ctrl:1
	v_mov_b32_dpp v75, v247 row_ror:8 row_mask:0xf bank_mask:0xf bound_ctrl:1
	v_cndmask_b32_e64 v96, v248, v72, s[18:19]
	v_cndmask_b32_e64 v97, v249, v73, s[18:19]
	v_cndmask_b32_e64 v98, v250, v74, s[18:19]
	v_cndmask_b32_e64 v99, v251, v75, s[18:19]
	v_lshl_add_u64 v[146:147], v[146:147], 0, s[88:89]
	global_store_dwordx4 v[146:147], v[96:99], off sc1
	s_nop 1
	s_cmp_eq_u32 s90, 0
	s_cbranch_scc1 .Lxd20_done
	v_add_u32_e32 v172, v178, v207
	v_ashrrev_i32_e32 v173, 31, v172
	v_lshlrev_b64 v[172:173], 1, v[172:173]
	v_lshl_add_u64 v[248:249], s[84:85], 0, v[172:173]
	v_or_b32_e32 v174, s41, v208
	s_mov_b32 s88, 0x8000
	s_mov_b32 s89, 0
	v_cvt_pk_bf16_f32 v228, v140, v141
	v_cvt_pk_bf16_f32 v229, v142, v143
	v_cvt_pk_bf16_f32 v230, v136, v137
	v_cvt_pk_bf16_f32 v231, v138, v139
	v_cvt_pk_bf16_f32 v232, v132, v133
	v_cvt_pk_bf16_f32 v233, v134, v135
	v_cvt_pk_bf16_f32 v234, v180, v181
	v_cvt_pk_bf16_f32 v235, v168, v169
	v_add_u32_e32 v172, 0, v174
	v_mov_b32_e32 v173, 0
	v_lshlrev_b64 v[250:251], 12, v[172:173]
	v_lshl_add_u64 v[250:251], v[248:249], 0, v[250:251]
	v_mov_b32_dpp v236, v232 row_ror:8 row_mask:0xf bank_mask:0xf bound_ctrl:1
	v_mov_b32_dpp v237, v233 row_ror:8 row_mask:0xf bank_mask:0xf bound_ctrl:1
	v_mov_b32_dpp v238, v234 row_ror:8 row_mask:0xf bank_mask:0xf bound_ctrl:1
	v_mov_b32_dpp v239, v235 row_ror:8 row_mask:0xf bank_mask:0xf bound_ctrl:1
	v_cndmask_b32_e64 v240, v236, v228, s[18:19]
	v_cndmask_b32_e64 v241, v237, v229, s[18:19]
	v_cndmask_b32_e64 v242, v238, v230, s[18:19]
	v_cndmask_b32_e64 v243, v239, v231, s[18:19]
	global_store_dwordx4 v[250:251], v[240:243], off sc1
	s_nop 1
	v_mov_b32_dpp v236, v228 row_ror:8 row_mask:0xf bank_mask:0xf bound_ctrl:1
	v_mov_b32_dpp v237, v229 row_ror:8 row_mask:0xf bank_mask:0xf bound_ctrl:1
	v_mov_b32_dpp v238, v230 row_ror:8 row_mask:0xf bank_mask:0xf bound_ctrl:1
	v_mov_b32_dpp v239, v231 row_ror:8 row_mask:0xf bank_mask:0xf bound_ctrl:1
	v_cndmask_b32_e64 v244, v232, v236, s[18:19]
	v_cndmask_b32_e64 v245, v233, v237, s[18:19]
	v_cndmask_b32_e64 v246, v234, v238, s[18:19]
	v_cndmask_b32_e64 v247, v235, v239, s[18:19]
	v_lshl_add_u64 v[250:251], v[250:251], 0, s[88:89]
	global_store_dwordx4 v[250:251], v[244:247], off sc1
	s_nop 1
	v_cvt_pk_bf16_f32 v228, v170, v171
	v_cvt_pk_bf16_f32 v229, v164, v165
	v_cvt_pk_bf16_f32 v230, v188, v189
	v_cvt_pk_bf16_f32 v231, v184, v185
	v_cvt_pk_bf16_f32 v232, v182, v183
	v_cvt_pk_bf16_f32 v233, v166, v167
	v_cvt_pk_bf16_f32 v234, v190, v191
	v_cvt_pk_bf16_f32 v235, v186, v187
	v_add_u32_e32 v172, 16, v174
	v_mov_b32_e32 v173, 0
	v_lshlrev_b64 v[250:251], 12, v[172:173]
	v_lshl_add_u64 v[250:251], v[248:249], 0, v[250:251]
	v_mov_b32_dpp v236, v232 row_ror:8 row_mask:0xf bank_mask:0xf bound_ctrl:1
	v_mov_b32_dpp v237, v233 row_ror:8 row_mask:0xf bank_mask:0xf bound_ctrl:1
	v_mov_b32_dpp v238, v234 row_ror:8 row_mask:0xf bank_mask:0xf bound_ctrl:1
	v_mov_b32_dpp v239, v235 row_ror:8 row_mask:0xf bank_mask:0xf bound_ctrl:1
	v_cndmask_b32_e64 v240, v236, v228, s[18:19]
	v_cndmask_b32_e64 v241, v237, v229, s[18:19]
	v_cndmask_b32_e64 v242, v238, v230, s[18:19]
	v_cndmask_b32_e64 v243, v239, v231, s[18:19]
	global_store_dwordx4 v[250:251], v[240:243], off sc1
	s_nop 1
	v_mov_b32_dpp v236, v228 row_ror:8 row_mask:0xf bank_mask:0xf bound_ctrl:1
	v_mov_b32_dpp v237, v229 row_ror:8 row_mask:0xf bank_mask:0xf bound_ctrl:1
	v_mov_b32_dpp v238, v230 row_ror:8 row_mask:0xf bank_mask:0xf bound_ctrl:1
	v_mov_b32_dpp v239, v231 row_ror:8 row_mask:0xf bank_mask:0xf bound_ctrl:1
	v_cndmask_b32_e64 v244, v232, v236, s[18:19]
; #define LAS __attribute__((address_space(3)))
; __device__ __forceinline__ unsigned cvt_pk_bf16(float lo, float hi) { const f32x2 v = {lo, hi}; const bf16x2_t b = __builtin_convertvector(v, bf16x2_t); return __builtin_bit_cast(unsigned, b); }
; __device__ __forceinline__ void store16_wt(void* p, u32x4 v) { asm volatile("global_store_dwordx4 %0, %1, off sc1\n\ts_nop 1" :: "v"(p), "v"(v) : "memory"); }
; __device__ __forceinline__ u32x4 ror8_u4(u32x4 v) { const unsigned a = ror8_u(v.x), b = ror8_u(v.y), c = ror8_u(v.z), d = ror8_u(v.w); return (u32x4){a, b, c, d}; }
;     __device__ __forceinline__ void epi(AccT& acc, const Unit& u, LAS unsigned char* lds, int wr, int wc, int fr, int fq) const {
;     ...
;                 for (int m = 0; m < 4; ++m) { const int r = ai * 128 + wr * 64 + m * 16 + fr; const float rs = bad ? qnan : Sl[r];
;                     const size_t rowA = (size_t)(u.pm * 256 + ai * 128 + wr * 64 + m * 16 + (fr & 7)); u32x4 p[2], q[2];
; #pragma unroll
;                     for (int bj = 0; bj < 2; ++bj) { const f32x4 x0 = acc[ai][bj][m][0], x1 = acc[ai][bj][m][1];
;                         const f32x4 h0 = x0 * rs * *(const LAS f32x4*)(svl + cl + bj * 32) + *(const LAS f32x4*)(tvl + cl + bj * 32), h1 = x1 * rs * *(const LAS f32x4*)(svl + cl + bj * 32 + 4) + *(const LAS f32x4*)(tvl + cl + bj * 32 + 4);
;                         p[bj].x = cvt_pk_bf16(h0[0], h0[1]); p[bj].y = cvt_pk_bf16(h0[2], h0[3]); p[bj].z = cvt_pk_bf16(h1[0], h1[1]); p[bj].w = cvt_pk_bf16(h1[2], h1[3]);
;                         q[bj].x = cvt_pk_bf16(x0[0], x0[1]); q[bj].y = cvt_pk_bf16(x0[2], x0[3]); q[bj].z = cvt_pk_bf16(x1[0], x1[1]); q[bj].w = cvt_pk_bf16(x1[2], x1[3]); }
;                     const u32x4 rq0 = ror8_u4(q[0]), rq1 = ror8_u4(q[1]), rp0 = ror8_u4(p[0]), rp1 = ror8_u4(p[1]);
;                     store16_wt(XHw + rowA * (2 * D) + colp, lo ? q[0] : rq1); store16_wt(XHw + (rowA + 8) * (2 * D) + colp, lo ? rq0 : q[1]);
;                     store16_wt(H + rowA * D + colp, lo ? p[0] : rp1); store16_wt(H + (rowA + 8) * D + colp, lo ? rp0 : p[1]); }
	v_cndmask_b32_e64 v245, v233, v237, s[18:19]
	v_cndmask_b32_e64 v246, v234, v238, s[18:19]
	v_cndmask_b32_e64 v247, v235, v239, s[18:19]
	v_lshl_add_u64 v[250:251], v[250:251], 0, s[88:89]
	global_store_dwordx4 v[250:251], v[244:247], off sc1
	s_nop 1
	v_cvt_pk_bf16_f32 v228, v130, v131
	v_cvt_pk_bf16_f32 v229, v128, v129
	v_cvt_pk_bf16_f32 v230, v160, v161
	v_cvt_pk_bf16_f32 v231, v158, v159
	v_cvt_pk_bf16_f32 v232, v156, v157
	v_cvt_pk_bf16_f32 v233, v148, v149
	v_cvt_pk_bf16_f32 v234, v162, v163
	v_cvt_pk_bf16_f32 v235, v150, v151
	v_add_u32_e32 v172, 32, v174
	v_mov_b32_e32 v173, 0
	v_lshlrev_b64 v[250:251], 12, v[172:173]
	v_lshl_add_u64 v[250:251], v[248:249], 0, v[250:251]
	v_mov_b32_dpp v236, v232 row_ror:8 row_mask:0xf bank_mask:0xf bound_ctrl:1
	v_mov_b32_dpp v237, v233 row_ror:8 row_mask:0xf bank_mask:0xf bound_ctrl:1
	v_mov_b32_dpp v238, v234 row_ror:8 row_mask:0xf bank_mask:0xf bound_ctrl:1
	v_mov_b32_dpp v239, v235 row_ror:8 row_mask:0xf bank_mask:0xf bound_ctrl:1
	v_cndmask_b32_e64 v240, v236, v228, s[18:19]
	v_cndmask_b32_e64 v241, v237, v229, s[18:19]
	v_cndmask_b32_e64 v242, v238, v230, s[18:19]
	v_cndmask_b32_e64 v243, v239, v231, s[18:19]
	global_store_dwordx4 v[250:251], v[240:243], off sc1
	s_nop 1
	v_mov_b32_dpp v236, v228 row_ror:8 row_mask:0xf bank_mask:0xf bound_ctrl:1
	v_mov_b32_dpp v237, v229 row_ror:8 row_mask:0xf bank_mask:0xf bound_ctrl:1
	v_mov_b32_dpp v238, v230 row_ror:8 row_mask:0xf bank_mask:0xf bound_ctrl:1
	v_mov_b32_dpp v239, v231 row_ror:8 row_mask:0xf bank_mask:0xf bound_ctrl:1
	v_cndmask_b32_e64 v244, v232, v236, s[18:19]
	v_cndmask_b32_e64 v245, v233, v237, s[18:19]
	v_cndmask_b32_e64 v246, v234, v238, s[18:19]
	v_cndmask_b32_e64 v247, v235, v239, s[18:19]
	v_lshl_add_u64 v[250:251], v[250:251], 0, s[88:89]
	global_store_dwordx4 v[250:251], v[244:247], off sc1
	s_nop 1
	v_cvt_pk_bf16_f32 v228, v84, v85
	v_cvt_pk_bf16_f32 v229, v80, v81
	v_cvt_pk_bf16_f32 v230, v92, v93
	v_cvt_pk_bf16_f32 v231, v88, v89
	v_cvt_pk_bf16_f32 v232, v86, v87
	v_cvt_pk_bf16_f32 v233, v82, v83
	v_cvt_pk_bf16_f32 v234, v94, v95
	v_cvt_pk_bf16_f32 v235, v90, v91
	v_add_u32_e32 v172, 48, v174
	v_mov_b32_e32 v173, 0
	v_lshlrev_b64 v[250:251], 12, v[172:173]
	v_lshl_add_u64 v[250:251], v[248:249], 0, v[250:251]
	v_mov_b32_dpp v236, v232 row_ror:8 row_mask:0xf bank_mask:0xf bound_ctrl:1
	v_mov_b32_dpp v237, v233 row_ror:8 row_mask:0xf bank_mask:0xf bound_ctrl:1
	v_mov_b32_dpp v238, v234 row_ror:8 row_mask:0xf bank_mask:0xf bound_ctrl:1
	v_mov_b32_dpp v239, v235 row_ror:8 row_mask:0xf bank_mask:0xf bound_ctrl:1
	v_cndmask_b32_e64 v240, v236, v228, s[18:19]
	v_cndmask_b32_e64 v241, v237, v229, s[18:19]
	v_cndmask_b32_e64 v242, v238, v230, s[18:19]
	v_cndmask_b32_e64 v243, v239, v231, s[18:19]
	global_store_dwordx4 v[250:251], v[240:243], off sc1
	s_nop 1
	v_mov_b32_dpp v236, v228 row_ror:8 row_mask:0xf bank_mask:0xf bound_ctrl:1
	v_mov_b32_dpp v237, v229 row_ror:8 row_mask:0xf bank_mask:0xf bound_ctrl:1
	v_mov_b32_dpp v238, v230 row_ror:8 row_mask:0xf bank_mask:0xf bound_ctrl:1
	v_mov_b32_dpp v239, v231 row_ror:8 row_mask:0xf bank_mask:0xf bound_ctrl:1
	v_cndmask_b32_e64 v244, v232, v236, s[18:19]
	v_cndmask_b32_e64 v245, v233, v237, s[18:19]
	v_cndmask_b32_e64 v246, v234, v238, s[18:19]
	v_cndmask_b32_e64 v247, v235, v239, s[18:19]
	v_lshl_add_u64 v[250:251], v[250:251], 0, s[88:89]
	global_store_dwordx4 v[250:251], v[244:247], off sc1
	s_nop 1
	v_cvt_pk_bf16_f32 v228, v60, v61
	v_cvt_pk_bf16_f32 v229, v62, v63
	v_cvt_pk_bf16_f32 v230, v56, v57
	v_cvt_pk_bf16_f32 v231, v58, v59
	v_cvt_pk_bf16_f32 v232, v52, v53
	v_cvt_pk_bf16_f32 v233, v54, v55
	v_cvt_pk_bf16_f32 v234, v48, v49
	v_cvt_pk_bf16_f32 v235, v50, v51
	v_add_u32_e32 v172, 0x80, v174
	v_mov_b32_e32 v173, 0
	v_lshlrev_b64 v[250:251], 12, v[172:173]
	v_lshl_add_u64 v[250:251], v[248:249], 0, v[250:251]
	v_mov_b32_dpp v236, v232 row_ror:8 row_mask:0xf bank_mask:0xf bound_ctrl:1
	v_mov_b32_dpp v237, v233 row_ror:8 row_mask:0xf bank_mask:0xf bound_ctrl:1
	v_mov_b32_dpp v238, v234 row_ror:8 row_mask:0xf bank_mask:0xf bound_ctrl:1
	v_mov_b32_dpp v239, v235 row_ror:8 row_mask:0xf bank_mask:0xf bound_ctrl:1
	v_cndmask_b32_e64 v240, v236, v228, s[18:19]
	v_cndmask_b32_e64 v241, v237, v229, s[18:19]
	v_cndmask_b32_e64 v242, v238, v230, s[18:19]
	v_cndmask_b32_e64 v243, v239, v231, s[18:19]
	global_store_dwordx4 v[250:251], v[240:243], off sc1
	s_nop 1
	v_mov_b32_dpp v236, v228 row_ror:8 row_mask:0xf bank_mask:0xf bound_ctrl:1
	v_mov_b32_dpp v237, v229 row_ror:8 row_mask:0xf bank_mask:0xf bound_ctrl:1
	v_mov_b32_dpp v238, v230 row_ror:8 row_mask:0xf bank_mask:0xf bound_ctrl:1
	v_mov_b32_dpp v239, v231 row_ror:8 row_mask:0xf bank_mask:0xf bound_ctrl:1
	v_cndmask_b32_e64 v244, v232, v236, s[18:19]
	v_cndmask_b32_e64 v245, v233, v237, s[18:19]
	v_cndmask_b32_e64 v246, v234, v238, s[18:19]
	v_cndmask_b32_e64 v247, v235, v239, s[18:19]
	v_lshl_add_u64 v[250:251], v[250:251], 0, s[88:89]
	global_store_dwordx4 v[250:251], v[244:247], off sc1
	s_nop 1
	v_cvt_pk_bf16_f32 v228, v44, v45
	v_cvt_pk_bf16_f32 v229, v46, v47
	v_cvt_pk_bf16_f32 v230, v40, v41
	v_cvt_pk_bf16_f32 v231, v42, v43
	v_cvt_pk_bf16_f32 v232, v36, v37
	v_cvt_pk_bf16_f32 v233, v38, v39
; #define LAS __attribute__((address_space(3)))
; __device__ __forceinline__ unsigned cvt_pk_bf16(float lo, float hi) { const f32x2 v = {lo, hi}; const bf16x2_t b = __builtin_convertvector(v, bf16x2_t); return __builtin_bit_cast(unsigned, b); }
; __device__ __forceinline__ void store16_wt(void* p, u32x4 v) { asm volatile("global_store_dwordx4 %0, %1, off sc1\n\ts_nop 1" :: "v"(p), "v"(v) : "memory"); }
; __device__ __forceinline__ u32x4 ror8_u4(u32x4 v) { const unsigned a = ror8_u(v.x), b = ror8_u(v.y), c = ror8_u(v.z), d = ror8_u(v.w); return (u32x4){a, b, c, d}; }
;     asm volatile("s_waitcnt vmcnt(0)" ::: "memory");
;     __syncthreads();
;     __device__ __forceinline__ void epi(AccT& acc, const Unit& u, LAS unsigned char* lds, int wr, int wc, int fr, int fq) const {
;     ...
;                 for (int m = 0; m < 4; ++m) { const int r = ai * 128 + wr * 64 + m * 16 + fr; const float rs = bad ? qnan : Sl[r];
;                     const size_t rowA = (size_t)(u.pm * 256 + ai * 128 + wr * 64 + m * 16 + (fr & 7)); u32x4 p[2], q[2];
; #pragma unroll
;                     for (int bj = 0; bj < 2; ++bj) { const f32x4 x0 = acc[ai][bj][m][0], x1 = acc[ai][bj][m][1];
;                         const f32x4 h0 = x0 * rs * *(const LAS f32x4*)(svl + cl + bj * 32) + *(const LAS f32x4*)(tvl + cl + bj * 32), h1 = x1 * rs * *(const LAS f32x4*)(svl + cl + bj * 32 + 4) + *(const LAS f32x4*)(tvl + cl + bj * 32 + 4);
;                         p[bj].x = cvt_pk_bf16(h0[0], h0[1]); p[bj].y = cvt_pk_bf16(h0[2], h0[3]); p[bj].z = cvt_pk_bf16(h1[0], h1[1]); p[bj].w = cvt_pk_bf16(h1[2], h1[3]);
;                         q[bj].x = cvt_pk_bf16(x0[0], x0[1]); q[bj].y = cvt_pk_bf16(x0[2], x0[3]); q[bj].z = cvt_pk_bf16(x1[0], x1[1]); q[bj].w = cvt_pk_bf16(x1[2], x1[3]); }
;                     const u32x4 rq0 = ror8_u4(q[0]), rq1 = ror8_u4(q[1]), rp0 = ror8_u4(p[0]), rp1 = ror8_u4(p[1]);
;                     store16_wt(XHw + rowA * (2 * D) + colp, lo ? q[0] : rq1); store16_wt(XHw + (rowA + 8) * (2 * D) + colp, lo ? rq0 : q[1]);
;                     store16_wt(H + rowA * D + colp, lo ? p[0] : rp1); store16_wt(H + (rowA + 8) * D + colp, lo ? rp0 : p[1]); }
	v_cvt_pk_bf16_f32 v234, v32, v33
	v_cvt_pk_bf16_f32 v235, v34, v35
	v_add_u32_e32 v172, 0x90, v174
	v_mov_b32_e32 v173, 0
	v_lshlrev_b64 v[250:251], 12, v[172:173]
	v_lshl_add_u64 v[250:251], v[248:249], 0, v[250:251]
	v_mov_b32_dpp v236, v232 row_ror:8 row_mask:0xf bank_mask:0xf bound_ctrl:1
	v_mov_b32_dpp v237, v233 row_ror:8 row_mask:0xf bank_mask:0xf bound_ctrl:1
	v_mov_b32_dpp v238, v234 row_ror:8 row_mask:0xf bank_mask:0xf bound_ctrl:1
	v_mov_b32_dpp v239, v235 row_ror:8 row_mask:0xf bank_mask:0xf bound_ctrl:1
	v_cndmask_b32_e64 v240, v236, v228, s[18:19]
	v_cndmask_b32_e64 v241, v237, v229, s[18:19]
	v_cndmask_b32_e64 v242, v238, v230, s[18:19]
	v_cndmask_b32_e64 v243, v239, v231, s[18:19]
	global_store_dwordx4 v[250:251], v[240:243], off sc1
	s_nop 1
	v_mov_b32_dpp v236, v228 row_ror:8 row_mask:0xf bank_mask:0xf bound_ctrl:1
	v_mov_b32_dpp v237, v229 row_ror:8 row_mask:0xf bank_mask:0xf bound_ctrl:1
	v_mov_b32_dpp v238, v230 row_ror:8 row_mask:0xf bank_mask:0xf bound_ctrl:1
	v_mov_b32_dpp v239, v231 row_ror:8 row_mask:0xf bank_mask:0xf bound_ctrl:1
	v_cndmask_b32_e64 v244, v232, v236, s[18:19]
	v_cndmask_b32_e64 v245, v233, v237, s[18:19]
	v_cndmask_b32_e64 v246, v234, v238, s[18:19]
	v_cndmask_b32_e64 v247, v235, v239, s[18:19]
	v_lshl_add_u64 v[250:251], v[250:251], 0, s[88:89]
	global_store_dwordx4 v[250:251], v[244:247], off sc1
	s_nop 1
	v_cvt_pk_bf16_f32 v228, v28, v29
	v_cvt_pk_bf16_f32 v229, v30, v31
	v_cvt_pk_bf16_f32 v230, v24, v25
	v_cvt_pk_bf16_f32 v231, v26, v27
	v_cvt_pk_bf16_f32 v232, v20, v21
	v_cvt_pk_bf16_f32 v233, v22, v23
	v_cvt_pk_bf16_f32 v234, v16, v17
	v_cvt_pk_bf16_f32 v235, v18, v19
	v_add_u32_e32 v172, 0xa0, v174
	v_mov_b32_e32 v173, 0
	v_lshlrev_b64 v[250:251], 12, v[172:173]
	v_lshl_add_u64 v[250:251], v[248:249], 0, v[250:251]
	v_mov_b32_dpp v236, v232 row_ror:8 row_mask:0xf bank_mask:0xf bound_ctrl:1
	v_mov_b32_dpp v237, v233 row_ror:8 row_mask:0xf bank_mask:0xf bound_ctrl:1
	v_mov_b32_dpp v238, v234 row_ror:8 row_mask:0xf bank_mask:0xf bound_ctrl:1
	v_mov_b32_dpp v239, v235 row_ror:8 row_mask:0xf bank_mask:0xf bound_ctrl:1
	v_cndmask_b32_e64 v240, v236, v228, s[18:19]
	v_cndmask_b32_e64 v241, v237, v229, s[18:19]
	v_cndmask_b32_e64 v242, v238, v230, s[18:19]
	v_cndmask_b32_e64 v243, v239, v231, s[18:19]
	global_store_dwordx4 v[250:251], v[240:243], off sc1
	s_nop 1
	v_mov_b32_dpp v236, v228 row_ror:8 row_mask:0xf bank_mask:0xf bound_ctrl:1
	v_mov_b32_dpp v237, v229 row_ror:8 row_mask:0xf bank_mask:0xf bound_ctrl:1
	v_mov_b32_dpp v238, v230 row_ror:8 row_mask:0xf bank_mask:0xf bound_ctrl:1
	v_mov_b32_dpp v239, v231 row_ror:8 row_mask:0xf bank_mask:0xf bound_ctrl:1
	v_cndmask_b32_e64 v244, v232, v236, s[18:19]
	v_cndmask_b32_e64 v245, v233, v237, s[18:19]
	v_cndmask_b32_e64 v246, v234, v238, s[18:19]
	v_cndmask_b32_e64 v247, v235, v239, s[18:19]
	v_lshl_add_u64 v[250:251], v[250:251], 0, s[88:89]
	global_store_dwordx4 v[250:251], v[244:247], off sc1
	s_nop 1
	v_cvt_pk_bf16_f32 v228, v12, v13
	v_cvt_pk_bf16_f32 v229, v14, v15
	v_cvt_pk_bf16_f32 v230, v8, v9
	v_cvt_pk_bf16_f32 v231, v10, v11
	v_cvt_pk_bf16_f32 v232, v4, v5
	v_cvt_pk_bf16_f32 v233, v6, v7
	v_cvt_pk_bf16_f32 v234, v0, v1
	v_cvt_pk_bf16_f32 v235, v2, v3
	v_add_u32_e32 v172, 0xb0, v174
	v_mov_b32_e32 v173, 0
	v_lshlrev_b64 v[250:251], 12, v[172:173]
	v_lshl_add_u64 v[250:251], v[248:249], 0, v[250:251]
	v_mov_b32_dpp v236, v232 row_ror:8 row_mask:0xf bank_mask:0xf bound_ctrl:1
	v_mov_b32_dpp v237, v233 row_ror:8 row_mask:0xf bank_mask:0xf bound_ctrl:1
	v_mov_b32_dpp v238, v234 row_ror:8 row_mask:0xf bank_mask:0xf bound_ctrl:1
	v_mov_b32_dpp v239, v235 row_ror:8 row_mask:0xf bank_mask:0xf bound_ctrl:1
	v_cndmask_b32_e64 v240, v236, v228, s[18:19]
	v_cndmask_b32_e64 v241, v237, v229, s[18:19]
	v_cndmask_b32_e64 v242, v238, v230, s[18:19]
	v_cndmask_b32_e64 v243, v239, v231, s[18:19]
	global_store_dwordx4 v[250:251], v[240:243], off sc1
	s_nop 1
	v_mov_b32_dpp v236, v228 row_ror:8 row_mask:0xf bank_mask:0xf bound_ctrl:1
	v_mov_b32_dpp v237, v229 row_ror:8 row_mask:0xf bank_mask:0xf bound_ctrl:1
	v_mov_b32_dpp v238, v230 row_ror:8 row_mask:0xf bank_mask:0xf bound_ctrl:1
	v_mov_b32_dpp v239, v231 row_ror:8 row_mask:0xf bank_mask:0xf bound_ctrl:1
	v_cndmask_b32_e64 v244, v232, v236, s[18:19]
	v_cndmask_b32_e64 v245, v233, v237, s[18:19]
	v_cndmask_b32_e64 v246, v234, v238, s[18:19]
	v_cndmask_b32_e64 v247, v235, v239, s[18:19]
	v_lshl_add_u64 v[250:251], v[250:251], 0, s[88:89]
	global_store_dwordx4 v[250:251], v[244:247], off sc1
	s_nop 1
.Lxd20_done:
	s_andn2_b64 vcc, exec, s[20:21]
	s_mov_b64 s[20:21], -1
	s_cbranch_vccnz .LBB0_629
	v_readlane_b32 s20, v252, 50
	v_readlane_b32 s21, v252, 51
	s_andn2_b64 vcc, exec, s[20:21]
	s_cbranch_vccnz .LBB0_628
	s_barrier
	s_branch .LBB0_628
.LBB0_702:
	s_cmp_eq_u32 s90, 0
	s_cbranch_scc0 .Lxd20_w1a
	s_waitcnt vmcnt(0)
	s_branch .Lxd20_w1b
.Lxd20_w1a:
	s_waitcnt vmcnt(16)
.Lxd20_w1b:
	v_readlane_b32 s94, v252, 46
	v_readlane_b32 s72, v252, 44
	v_readlane_b32 s3, v252, 61
	v_readlane_b32 s92, v252, 48
	v_readlane_b32 s95, v252, 47
	v_readlane_b32 s68, v252, 38
	s_getpc_b64 s[28:29]
	v_readlane_b32 s73, v252, 45
	s_mov_b64 s[6:7], 0
	s_barrier
	v_readlane_b32 s93, v252, 49

; __device__ __forceinline__ int lane_id() { return (int)__builtin_amdgcn_mbcnt_hi(~0u, __builtin_amdgcn_mbcnt_lo(~0u, 0u)); }
;     ...
;     if (b.wave == 1) {
;         const volatile unsigned* cp = (const volatile unsigned*)(__builtin_amdgcn_s_getpc() + (unsigned long long)lane_id() * 64ull); unsigned acc_ = 0u;
; #pragma unroll
;         for (int i = 0; i < 6; ++i) acc_ += cp[i * 1024];
;         asm volatile("" :: "v"(acc_));
;     }
;     if (b.wave >= 2 && pfb != nullptr) {
;         const int t_ = (b.wave - 2) * 64 + lane_id(); unsigned a_ = 0u;
; #pragma unroll
;         for (int i = 0; i < 3; ++i) { const int pc_ = t_ + 384 * i; if (pc_ < 1024) a_ += *(const volatile unsigned*)(pfb + (size_t)(pc_ >> 2) * pfp + (pc_ & 3) * 64); }
;         asm volatile("" :: "v"(a_));
;     }
.Lxd20_w2b:
	v_readlane_b32 s0, v252, 34
	v_readlane_b32 s1, v252, 35
	s_and_b64 vcc, exec, s[0:1]
	s_barrier
	s_cbranch_vccnz .LBB0_707
	v_mbcnt_lo_u32_b32 v0, -1, 0
	v_mbcnt_hi_u32_b32 v0, -1, v0
	v_lshlrev_b32_e32 v0, 6, v0
	v_mov_b32_e32 v1, 0
	v_lshl_add_u64 v[0:1], v[0:1], 0, s[28:29]
	v_add_co_u32_e32 v2, vcc, 0x1000, v0
	global_load_dword v248, v[0:1], off sc0 sc1
	s_nop 0
	v_addc_co_u32_e32 v3, vcc, 0, v1, vcc
	global_load_dword v249, v[2:3], off sc0 sc1
	s_nop 0
	v_add_co_u32_e32 v2, vcc, 0x2000, v0
	s_nop 1
	v_addc_co_u32_e32 v3, vcc, 0, v1, vcc
	global_load_dword v250, v[2:3], off sc0 sc1
	s_nop 0
	v_add_co_u32_e32 v2, vcc, 0x3000, v0
	s_nop 1
	v_addc_co_u32_e32 v3, vcc, 0, v1, vcc
	global_load_dword v251, v[2:3], off sc0 sc1
	s_nop 0
	v_add_co_u32_e32 v2, vcc, 0x4000, v0
	s_nop 1
	v_addc_co_u32_e32 v3, vcc, 0, v1, vcc
	v_add_co_u32_e32 v0, vcc, 0x5000, v0
	global_load_dword v248, v[2:3], off sc0 sc1
	s_nop 0
	v_addc_co_u32_e32 v1, vcc, 0, v1, vcc
	global_load_dword v249, v[0:1], off sc0 sc1
	s_nop 0
.LBB0_707:
	v_readlane_b32 s4, v252, 40
	s_add_u32 s0, s34, 0x800000
	v_readlane_b32 s5, v252, 41
	s_addc_u32 s1, s35, 0
	s_and_b64 vcc, exec, s[4:5]
	s_cbranch_vccnz .LBB0_715
	s_add_u32 s4, s0, s6
	s_addc_u32 s5, s1, s7
	s_and_b32 s6, s90, 0xffffffc0
	v_mbcnt_lo_u32_b32 v0, -1, 0
	s_addk_i32 s6, 0xff80
	v_mbcnt_hi_u32_b32 v0, -1, v0
	v_add_u32_e32 v4, s6, v0
	v_lshlrev_b32_e32 v0, 6, v0
	v_mov_b32_e32 v1, 0
	v_and_b32_e32 v0, 0xc0, v0
	v_lshl_add_u64 v[2:3], s[4:5], 0, v[0:1]
	s_movk_i32 s4, 0x400
	v_cmp_gt_i32_e32 vcc, s4, v4
	s_and_saveexec_b64 s[8:9], vcc
	s_cbranch_execz .LBB0_710
	v_ashrrev_i32_e32 v0, 2, v4
	v_ashrrev_i32_e32 v1, 31, v0
	v_lshlrev_b64 v[0:1], 11, v[0:1]
	v_lshl_add_u64 v[0:1], v[2:3], 0, v[0:1]
	global_load_dword v248, v[0:1], off sc0 sc1
	s_nop 0
.LBB0_710:
	s_or_b64 exec, exec, s[8:9]
	s_movk_i32 s4, 0x280
	v_cmp_gt_i32_e32 vcc, s4, v4
	s_and_saveexec_b64 s[8:9], vcc
	s_cbranch_execz .LBB0_712
	v_add_u32_e32 v0, 0x180, v4
	v_ashrrev_i32_e32 v6, 2, v0
	v_ashrrev_i32_e32 v7, 31, v6
	v_lshlrev_b64 v[6:7], 11, v[6:7]
	v_lshl_add_u64 v[6:7], v[2:3], 0, v[6:7]
	global_load_dword v249, v[6:7], off sc0 sc1
	s_nop 0
.LBB0_712:
	s_or_b64 exec, exec, s[8:9]
	s_movk_i32 s4, 0x100
	v_cmp_gt_i32_e32 vcc, s4, v4
	s_and_saveexec_b64 s[8:9], vcc
	s_cbranch_execz .LBB0_714
	v_add_u32_e32 v0, 0x300, v4
	v_ashrrev_i32_e32 v4, 2, v0
	v_ashrrev_i32_e32 v5, 31, v4
	v_lshlrev_b64 v[4:5], 11, v[4:5]
	v_lshl_add_u64 v[2:3], v[2:3], 0, v[4:5]
	global_load_dword v250, v[2:3], off sc0 sc1
	s_nop 0
